# p14 with the E1/O1 transposed stores issued one step later (second chunk permuted into a second spare quad, bpermute latency hidden)
# baseline (speedup 1.0000x reference)
.Lalign_skip_0:
	v_pk_mul_f32 v[122:123], v[122:123], v[0:1] op_sel_hi:[1,0]
	v_add_f32_e32 v153, v153, v154
	v_mul_f32_e32 v178, 0x3d372713, v122
	v_add_f32_e32 v152, v152, v153
	v_mul_f32_e32 v177, 0x3fcc422a, v122
	v_fma_f32 v178, v122, v178, 1.0
	v_add_f32_e32 v151, v151, v152
	v_mul_f32_e32 v177, v177, v178
	v_mov_b32_e32 v152, v151
	v_mul_f32_e32 v177, 0xbfb8aa3b, v177
	s_nop 0
	v_permlane16_swap_b32_e32 v151, v152
	v_exp_f32_e32 v177, v177
	v_add_f32_e32 v175, v151, v152
	ds_read_b128 v[152:155], v167 offset:2048
	v_mul_f32_e32 v178, 0x3d372713, v123
	v_add_f32_e32 v177, 1.0, v177
	v_rcp_f32_e32 v177, v177
	v_fma_f32 v178, v123, v178, 1.0
	s_waitcnt lgkmcnt(0)
	v_lshlrev_b32_e32 v151, 16, v152
	v_and_b32_e32 v152, 0xffff0000, v152
	v_add_f32_e32 v151, v151, v152
	v_lshlrev_b32_e32 v152, 16, v153
	v_and_b32_e32 v153, 0xffff0000, v153
	v_add_f32_e32 v152, v152, v153
	v_add_f32_e32 v151, v151, v152
	v_lshlrev_b32_e32 v152, 16, v154
	v_and_b32_e32 v153, 0xffff0000, v154
	v_mul_f32_e32 v122, v122, v177
	v_mul_f32_e32 v177, 0x3fcc422a, v123
	v_add_f32_e32 v152, v152, v153
	v_lshlrev_b32_e32 v153, 16, v155
	v_and_b32_e32 v154, 0xffff0000, v155
	v_mul_f32_e32 v177, v177, v178
	v_add_f32_e32 v153, v153, v154
	v_mul_f32_e32 v177, 0xbfb8aa3b, v177
	v_add_f32_e32 v152, v152, v153
	v_exp_f32_e32 v177, v177
	v_add_f32_e32 v151, v151, v152
	v_mov_b32_e32 v152, v151
	s_nop 1
	v_permlane16_swap_b32_e32 v151, v152
	v_add_f32_e32 v173, v151, v152
	ds_read_b128 v[152:155], v167 offset:3072
	v_add_f32_e32 v177, 1.0, v177
	v_rcp_f32_e32 v177, v177
	v_pk_mul_f32 v[124:125], v[124:125], v[0:1] op_sel_hi:[1,0]
	v_pk_mul_f32 v[126:127], v[126:127], v[0:1] op_sel_hi:[1,0]
	v_mul_f32_e32 v178, 0x3d372713, v124
	s_waitcnt lgkmcnt(0)
	v_lshlrev_b32_e32 v151, 16, v152
	v_and_b32_e32 v152, 0xffff0000, v152
	v_mul_f32_e32 v123, v123, v177
	v_mul_f32_e32 v177, 0x3fcc422a, v124
	v_fma_f32 v178, v124, v178, 1.0
	v_add_f32_e32 v151, v151, v152
	v_lshlrev_b32_e32 v152, 16, v153
	v_and_b32_e32 v153, 0xffff0000, v153
	v_mul_f32_e32 v177, v177, v178
	v_add_f32_e32 v152, v152, v153
	v_mul_f32_e32 v177, 0xbfb8aa3b, v177
	v_add_f32_e32 v151, v151, v152
	v_lshlrev_b32_e32 v152, 16, v154
	v_and_b32_e32 v153, 0xffff0000, v154
	v_exp_f32_e32 v177, v177
	v_add_f32_e32 v152, v152, v153
	v_lshlrev_b32_e32 v153, 16, v155
	v_and_b32_e32 v154, 0xffff0000, v155
	v_add_f32_e32 v153, v153, v154
	v_add_f32_e32 v152, v152, v153
	v_add_f32_e32 v151, v151, v152
	v_add_f32_e32 v177, 1.0, v177
	v_mov_b32_e32 v152, v151
	v_rcp_f32_e32 v177, v177
	s_nop 0
	v_permlane16_swap_b32_e32 v151, v152
	v_add_f32_e32 v171, v151, v152
	ds_read_b128 v[152:155], v167 offset:8192
	v_mul_f32_e32 v178, 0x3d372713, v125
	v_mul_f32_e32 v124, v124, v177
	v_mul_f32_e32 v177, 0x3fcc422a, v125
	v_fma_f32 v178, v125, v178, 1.0
	v_mul_f32_e32 v177, v177, v178
	v_mul_f32_e32 v177, 0xbfb8aa3b, v177
	s_waitcnt lgkmcnt(0)
	v_lshlrev_b32_e32 v151, 16, v152
	v_and_b32_e32 v152, 0xffff0000, v152
	v_exp_f32_e32 v177, v177
	v_add_f32_e32 v151, v151, v152
	v_lshlrev_b32_e32 v152, 16, v153
	v_and_b32_e32 v153, 0xffff0000, v153
	v_add_f32_e32 v152, v152, v153
	v_add_f32_e32 v151, v151, v152
	v_lshlrev_b32_e32 v152, 16, v154
	v_and_b32_e32 v153, 0xffff0000, v154
	v_add_f32_e32 v152, v152, v153
	v_lshlrev_b32_e32 v153, 16, v155
	v_and_b32_e32 v154, 0xffff0000, v155
	v_add_f32_e32 v177, 1.0, v177
	v_add_f32_e32 v153, v153, v154
	v_rcp_f32_e32 v177, v177
	v_add_f32_e32 v152, v152, v153
	v_add_f32_e32 v151, v151, v152
	v_mov_b32_e32 v152, v151
	v_mul_f32_e32 v178, 0x3d372713, v126
	s_nop 0
	v_permlane16_swap_b32_e32 v151, v152
	v_mul_f32_e32 v125, v125, v177
	v_mul_f32_e32 v177, 0x3fcc422a, v126
	v_fma_f32 v178, v126, v178, 1.0
	v_add_f32_e32 v169, v151, v152
	ds_read_b128 v[152:155], v167 offset:9216
	v_mul_f32_e32 v177, v177, v178
	v_mul_f32_e32 v177, 0xbfb8aa3b, v177
	v_exp_f32_e32 v177, v177
	v_mul_f32_e32 v178, 0x3d372713, v127
	s_waitcnt lgkmcnt(0)
	v_lshlrev_b32_e32 v151, 16, v152
	v_and_b32_e32 v152, 0xffff0000, v152
	v_add_f32_e32 v151, v151, v152
	v_lshlrev_b32_e32 v152, 16, v153
	v_and_b32_e32 v153, 0xffff0000, v153
	v_add_f32_e32 v177, 1.0, v177
	v_add_f32_e32 v152, v152, v153
	v_rcp_f32_e32 v177, v177
	v_add_f32_e32 v151, v151, v152
	v_lshlrev_b32_e32 v152, 16, v154
	v_and_b32_e32 v153, 0xffff0000, v154
	v_add_f32_e32 v152, v152, v153
	v_lshlrev_b32_e32 v153, 16, v155
	v_and_b32_e32 v154, 0xffff0000, v155
	v_add_f32_e32 v153, v153, v154
	v_add_f32_e32 v152, v152, v153
	v_mul_f32_e32 v126, v126, v177
	v_mul_f32_e32 v177, 0x3fcc422a, v127
	v_fma_f32 v178, v127, v178, 1.0
	v_add_f32_e32 v151, v151, v152
	v_mul_f32_e32 v177, v177, v178
	v_mov_b32_e32 v152, v151
	v_mul_f32_e32 v177, 0xbfb8aa3b, v177
	s_nop 0
	v_permlane16_swap_b32_e32 v151, v152
	v_exp_f32_e32 v177, v177
	v_add_f32_e32 v161, v151, v152
	ds_read_b128 v[152:155], v167 offset:10240
	v_pk_mul_f32 v[128:129], v[128:129], v[0:1] op_sel_hi:[1,0]
	v_add_f32_e32 v177, 1.0, v177
	v_rcp_f32_e32 v177, v177
	v_mul_f32_e32 v178, 0x3d372713, v128
	s_waitcnt lgkmcnt(0)
	v_lshlrev_b32_e32 v151, 16, v152
	v_and_b32_e32 v152, 0xffff0000, v152
	v_add_f32_e32 v151, v151, v152
	v_lshlrev_b32_e32 v152, 16, v153
	v_and_b32_e32 v153, 0xffff0000, v153
	v_add_f32_e32 v152, v152, v153
	v_add_f32_e32 v151, v151, v152
	v_lshlrev_b32_e32 v152, 16, v154
	v_and_b32_e32 v153, 0xffff0000, v154
	v_mul_f32_e32 v127, v127, v177
	v_mul_f32_e32 v177, 0x3fcc422a, v128
	v_fma_f32 v178, v128, v178, 1.0
	v_add_f32_e32 v152, v152, v153
	v_lshlrev_b32_e32 v153, 16, v155
	v_and_b32_e32 v154, 0xffff0000, v155
	v_mul_f32_e32 v177, v177, v178
	v_add_f32_e32 v153, v153, v154
	v_mul_f32_e32 v177, 0xbfb8aa3b, v177
	v_add_f32_e32 v152, v152, v153
	v_exp_f32_e32 v177, v177
	v_add_f32_e32 v151, v151, v152
	v_mov_b32_e32 v152, v151
	s_nop 1
	v_permlane16_swap_b32_e32 v151, v152
	v_add_f32_e32 v159, v151, v152
	ds_read_b128 v[152:155], v167 offset:11264
	v_add_f32_e32 v177, 1.0, v177
	v_rcp_f32_e32 v177, v177
	v_mul_f32_e32 v178, 0x3d372713, v129
	v_fma_f32 v178, v129, v178, 1.0
	s_waitcnt lgkmcnt(0)
	v_lshlrev_b32_e32 v151, 16, v152
	v_and_b32_e32 v152, 0xffff0000, v152
	v_mul_f32_e32 v128, v128, v177
	v_mul_f32_e32 v177, 0x3fcc422a, v129
	v_add_f32_e32 v151, v151, v152
	v_lshlrev_b32_e32 v152, 16, v153
	v_and_b32_e32 v153, 0xffff0000, v153
	v_mul_f32_e32 v177, v177, v178
	v_add_f32_e32 v152, v152, v153
	v_mul_f32_e32 v177, 0xbfb8aa3b, v177
	v_add_f32_e32 v151, v151, v152
	v_lshlrev_b32_e32 v152, 16, v154
	v_and_b32_e32 v153, 0xffff0000, v154
	v_exp_f32_e32 v177, v177
	v_add_f32_e32 v152, v152, v153
	v_lshlrev_b32_e32 v153, 16, v155
	v_and_b32_e32 v154, 0xffff0000, v155
	v_add_f32_e32 v153, v153, v154
	v_add_f32_e32 v152, v152, v153
	v_add_f32_e32 v151, v151, v152
	v_add_f32_e32 v177, 1.0, v177
	v_mov_b32_e32 v152, v151
	v_rcp_f32_e32 v177, v177
	s_nop 0
	v_permlane16_swap_b32_e32 v151, v152
	v_add_f32_e32 v157, v151, v152
	v_lshl_or_b32 v152, s12, 8, v165
	v_ashrrev_i32_e32 v153, 31, v152
	v_ashrrev_i32_e32 v151, 31, v150
	v_lshl_add_u64 v[152:153], v[152:153], 1, v[140:141]
	v_lshlrev_b64 v[154:155], 13, v[150:151]
	v_mul_f32_e32 v129, v129, v177
	v_mul_f32_e32 v177, v123, v123
	v_lshl_add_u64 v[154:155], v[152:153], 0, v[154:155]
	v_fmac_f32_e32 v177, v122, v122
	v_mul_f32_e32 v178, v125, v125
	v_cvt_pk_bf16_f32 v122, v122, v123
	v_pk_mul_f32 v[114:115], v[114:115], v[0:1] op_sel_hi:[1,0]
	v_fmac_f32_e32 v178, v124, v124
	v_cvt_pk_bf16_f32 v123, v124, v125
	v_cvt_pk_bf16_f32 v124, v126, v127
	v_cvt_pk_bf16_f32 v125, v128, v129
	ds_bpermute_b32 v250, v255, v122
	ds_bpermute_b32 v251, v255, v123
	ds_bpermute_b32 v252, v255, v124
	ds_bpermute_b32 v253, v255, v125
	v_pk_mul_f32 v[116:117], v[116:117], v[0:1] op_sel_hi:[1,0]
	v_pk_mul_f32 v[120:121], v[120:121], v[0:1] op_sel_hi:[1,0]
	v_mul_f32_e32 v122, 0x3d372713, v114
	v_pk_mul_f32 v[118:119], v[118:119], v[0:1] op_sel_hi:[1,0]
	v_mul_f32_e32 v0, 0x3fcc422a, v114
	v_fma_f32 v122, v114, v122, 1.0
	v_mul_f32_e32 v0, v0, v122
	v_mul_f32_e32 v0, 0xbfb8aa3b, v0
	v_exp_f32_e32 v0, v0
	v_mul_f32_e32 v122, 0x3d372713, v115
	v_fma_f32 v122, v115, v122, 1.0
	v_add_f32_e32 v177, v177, v178
	v_add_f32_e32 v0, 1.0, v0
	v_rcp_f32_e32 v0, v0
	v_mul_f32_e32 v178, v127, v127
	v_mul_f32_e32 v179, v129, v129
	v_fmac_f32_e32 v178, v126, v126
	v_mul_f32_e32 v0, v114, v0
	v_mul_f32_e32 v114, 0x3fcc422a, v115
	v_mul_f32_e32 v114, v114, v122
	v_mul_f32_e32 v114, 0xbfb8aa3b, v114
	v_exp_f32_e32 v114, v114
	v_mul_f32_e32 v122, 0x3d372713, v116
	v_fma_f32 v122, v116, v122, 1.0
	v_fmac_f32_e32 v179, v128, v128
	v_add_f32_e32 v114, 1.0, v114
	v_rcp_f32_e32 v114, v114
	v_add_f32_e32 v178, v178, v179
	v_add_f32_e32 v177, v177, v178
	v_mov_b32_e32 v176, v175
	v_mul_f32_e32 v114, v115, v114
	v_mul_f32_e32 v115, 0x3fcc422a, v116
	v_mul_f32_e32 v115, v115, v122
	v_mul_f32_e32 v115, 0xbfb8aa3b, v115
	v_exp_f32_e32 v115, v115
	v_mul_f32_e32 v122, 0x3d372713, v117
	v_fma_f32 v122, v117, v122, 1.0
	v_mov_b32_e32 v174, v173
	v_add_f32_e32 v115, 1.0, v115
	v_rcp_f32_e32 v115, v115
	v_mov_b32_e32 v172, v171
	v_mov_b32_e32 v170, v169
	v_mov_b32_e32 v168, v161
	v_mul_f32_e32 v115, v116, v115
	v_mul_f32_e32 v116, 0x3fcc422a, v117
	v_mul_f32_e32 v116, v116, v122
	v_mul_f32_e32 v116, 0xbfb8aa3b, v116
	v_exp_f32_e32 v116, v116
	v_mul_f32_e32 v122, 0x3d372713, v118
	v_fma_f32 v122, v118, v122, 1.0
	v_mov_b32_e32 v160, v159
	v_add_f32_e32 v116, 1.0, v116
	v_rcp_f32_e32 v116, v116
	v_mov_b32_e32 v158, v157
	v_permlane32_swap_b32_e32 v175, v176
	v_mul_f32_e32 v116, v117, v116
	v_mul_f32_e32 v117, 0x3fcc422a, v118
	v_mul_f32_e32 v117, v117, v122
	v_mul_f32_e32 v117, 0xbfb8aa3b, v117
	v_exp_f32_e32 v117, v117
	v_mul_f32_e32 v122, 0x3d372713, v119
	v_fma_f32 v122, v119, v122, 1.0
	v_permlane32_swap_b32_e32 v173, v174
	v_add_f32_e32 v117, 1.0, v117
	v_rcp_f32_e32 v117, v117
	v_permlane32_swap_b32_e32 v171, v172
	v_permlane32_swap_b32_e32 v169, v170
	v_mul_f32_e32 v117, v118, v117
	v_mul_f32_e32 v118, 0x3fcc422a, v119
	v_mul_f32_e32 v118, v118, v122
	v_mul_f32_e32 v118, 0xbfb8aa3b, v118
	v_exp_f32_e32 v118, v118
	v_mul_f32_e32 v122, 0x3d372713, v120
	v_fma_f32 v122, v120, v122, 1.0
	v_permlane32_swap_b32_e32 v161, v168
	v_add_f32_e32 v118, 1.0, v118
	v_rcp_f32_e32 v118, v118
	v_permlane32_swap_b32_e32 v159, v160
	v_permlane32_swap_b32_e32 v157, v158
	v_mul_f32_e32 v118, v119, v118
	v_mul_f32_e32 v119, 0x3fcc422a, v120
	v_mul_f32_e32 v119, v119, v122
	v_mul_f32_e32 v119, 0xbfb8aa3b, v119
	v_exp_f32_e32 v119, v119
	v_mul_f32_e32 v122, 0x3d372713, v121
	v_fma_f32 v122, v121, v122, 1.0
	v_add_f32_e32 v119, 1.0, v119
	v_rcp_f32_e32 v119, v119
	s_nop 0
	v_mul_f32_e32 v119, v120, v119
	v_mul_f32_e32 v120, 0x3fcc422a, v121
	v_mul_f32_e32 v120, v120, v122
	v_mul_f32_e32 v120, 0xbfb8aa3b, v120
	v_exp_f32_e32 v120, v120
	v_mul_f32_e32 v122, v116, v116
	v_fmac_f32_e32 v122, v115, v115
	v_add_f32_e32 v120, 1.0, v120
	v_rcp_f32_e32 v120, v120
	s_nop 0
	v_mul_f32_e32 v120, v121, v120
	v_mul_f32_e32 v121, v114, v114
	v_fmac_f32_e32 v121, v0, v0
	v_add_f32_e32 v121, v121, v122
	v_mul_f32_e32 v122, v118, v118
	v_mul_f32_e32 v123, v120, v120
	v_fmac_f32_e32 v122, v117, v117
	v_fmac_f32_e32 v123, v119, v119
	v_add_f32_e32 v122, v122, v123
	v_add_f32_e32 v121, v121, v122
	v_add_f32_e32 v121, v177, v121
	v_cvt_pk_bf16_f32 v114, v0, v114
	v_mov_b32_e32 v0, v121
	s_nop 1
	v_permlane16_swap_b32_e32 v121, v0
	v_add_f32_e32 v0, v121, v0
	v_cvt_pk_bf16_f32 v115, v115, v116
	v_cvt_pk_bf16_f32 v116, v117, v118
	v_cvt_pk_bf16_f32 v117, v119, v120
	ds_bpermute_b32 v244, v255, v114
	ds_bpermute_b32 v245, v255, v115
	ds_bpermute_b32 v246, v255, v116
	ds_bpermute_b32 v247, v255, v117
	v_lshl_add_u64 v[248:249], v[154:155], 0, v[208:209]
	s_waitcnt lgkmcnt(4)
	global_store_dwordx4 v[248:249], v[250:253], off
	s_nop 1
	v_mov_b32_e32 v114, v0
	s_nop 1
	v_permlane32_swap_b32_e32 v0, v114
	s_and_saveexec_b64 s[0:1], s[2:3]
	s_cbranch_execz .LBB0_175
	v_add_f32_e32 v0, v0, v114
	v_lshlrev_b64 v[114:115], 7, v[150:151]
	s_lshl_b32 s36, s12, 2
	v_lshl_add_u64 v[114:115], v[138:139], 0, v[114:115]
	s_mov_b32 s37, s40
	v_lshl_add_u64 v[114:115], s[36:37], 2, v[114:115]
	s_lshl_b32 s36, s28, 2
	v_lshl_add_u64 v[114:115], v[114:115], 0, s[36:37]
	global_store_dword v[114:115], v0, off offset:-128
.LBB0_175:
	s_or_b64 exec, exec, s[0:1]
	v_add_f32_e32 v0, v175, v176
	v_fmamk_f32 v0, v0, 0x3a000000, v240
	v_rsq_f32_e32 v0, v0
	v_or_b32_e32 v114, 16, v150
	v_ashrrev_i32_e32 v115, 31, v114
	v_lshlrev_b64 v[116:117], 13, v[114:115]
	v_pk_mul_f32 v[106:107], v[106:107], v[0:1] op_sel_hi:[1,0]
	v_pk_mul_f32 v[108:109], v[108:109], v[0:1] op_sel_hi:[1,0]
	v_mul_f32_e32 v119, 0x3d372713, v106
	v_mul_f32_e32 v118, 0x3fcc422a, v106
	v_fma_f32 v119, v106, v119, 1.0
	v_mul_f32_e32 v118, v118, v119
	v_mul_f32_e32 v118, 0xbfb8aa3b, v118
	v_exp_f32_e32 v118, v118
	v_mul_f32_e32 v119, 0x3d372713, v107
	v_fma_f32 v119, v107, v119, 1.0
	v_pk_mul_f32 v[110:111], v[110:111], v[0:1] op_sel_hi:[1,0]
	v_add_f32_e32 v118, 1.0, v118
	v_rcp_f32_e32 v118, v118
	v_pk_mul_f32 v[112:113], v[112:113], v[0:1] op_sel_hi:[1,0]
	v_lshl_add_u64 v[116:117], v[152:153], 0, v[116:117]
	v_pk_mul_f32 v[98:99], v[98:99], v[0:1] op_sel_hi:[1,0]
	v_mul_f32_e32 v106, v106, v118
	v_mul_f32_e32 v118, 0x3fcc422a, v107
	v_mul_f32_e32 v118, v118, v119
	v_mul_f32_e32 v118, 0xbfb8aa3b, v118
	v_exp_f32_e32 v118, v118
	v_mul_f32_e32 v119, 0x3d372713, v108
	v_fma_f32 v119, v108, v119, 1.0
	v_pk_mul_f32 v[100:101], v[100:101], v[0:1] op_sel_hi:[1,0]
	v_add_f32_e32 v118, 1.0, v118
	v_rcp_f32_e32 v118, v118
	v_pk_mul_f32 v[104:105], v[104:105], v[0:1] op_sel_hi:[1,0]
	v_pk_mul_f32 v[102:103], v[102:103], v[0:1] op_sel_hi:[1,0]
	v_mul_f32_e32 v0, 0x3fcc422a, v98
	v_mul_f32_e32 v107, v107, v118
	v_mul_f32_e32 v118, 0x3fcc422a, v108
	v_mul_f32_e32 v118, v118, v119
	v_mul_f32_e32 v118, 0xbfb8aa3b, v118
	v_exp_f32_e32 v118, v118
	v_mul_f32_e32 v119, 0x3d372713, v109
	v_fma_f32 v119, v109, v119, 1.0
	v_add_f32_e32 v118, 1.0, v118
	v_rcp_f32_e32 v118, v118
	s_nop 0
	v_mul_f32_e32 v108, v108, v118
	v_mul_f32_e32 v118, 0x3fcc422a, v109
	v_mul_f32_e32 v118, v118, v119
	v_mul_f32_e32 v118, 0xbfb8aa3b, v118
	v_exp_f32_e32 v118, v118
	v_mul_f32_e32 v119, 0x3d372713, v110
	v_fma_f32 v119, v110, v119, 1.0
	v_add_f32_e32 v118, 1.0, v118
	v_rcp_f32_e32 v118, v118
	s_nop 0
	v_mul_f32_e32 v109, v109, v118
	v_mul_f32_e32 v118, 0x3fcc422a, v110
	v_mul_f32_e32 v118, v118, v119
	v_mul_f32_e32 v118, 0xbfb8aa3b, v118
	v_exp_f32_e32 v118, v118
	v_mul_f32_e32 v119, 0x3d372713, v111
	v_fma_f32 v119, v111, v119, 1.0
	v_add_f32_e32 v118, 1.0, v118
	v_rcp_f32_e32 v118, v118
	s_nop 0
	v_mul_f32_e32 v110, v110, v118
	v_mul_f32_e32 v118, 0x3fcc422a, v111
	v_mul_f32_e32 v118, v118, v119
	v_mul_f32_e32 v118, 0xbfb8aa3b, v118
	v_exp_f32_e32 v118, v118
	v_mul_f32_e32 v119, 0x3d372713, v112
	v_fma_f32 v119, v112, v119, 1.0
	v_add_f32_e32 v118, 1.0, v118
	v_rcp_f32_e32 v118, v118
	s_nop 0
	v_mul_f32_e32 v111, v111, v118
	v_mul_f32_e32 v118, 0x3fcc422a, v112
	v_mul_f32_e32 v118, v118, v119
	v_mul_f32_e32 v118, 0xbfb8aa3b, v118
	v_exp_f32_e32 v118, v118
	v_mul_f32_e32 v119, 0x3d372713, v113
	v_fma_f32 v119, v113, v119, 1.0
	v_add_f32_e32 v118, 1.0, v118
	v_rcp_f32_e32 v118, v118
	s_nop 0
	v_mul_f32_e32 v112, v112, v118
	v_mul_f32_e32 v118, 0x3fcc422a, v113
	v_mul_f32_e32 v118, v118, v119
	v_mul_f32_e32 v118, 0xbfb8aa3b, v118
	v_exp_f32_e32 v118, v118
	v_mul_f32_e32 v119, v109, v109
	v_fmac_f32_e32 v119, v108, v108
	v_add_f32_e32 v118, 1.0, v118
	v_rcp_f32_e32 v118, v118
	s_nop 0
	v_mul_f32_e32 v113, v113, v118
	v_mul_f32_e32 v118, v107, v107
	v_fmac_f32_e32 v118, v106, v106
	v_cvt_pk_bf16_f32 v106, v106, v107
	v_cvt_pk_bf16_f32 v107, v108, v109
	v_cvt_pk_bf16_f32 v108, v110, v111
	v_cvt_pk_bf16_f32 v109, v112, v113
	s_waitcnt lgkmcnt(0)
	global_store_dwordx4 v[248:249], v[244:247], off offset:256
	ds_bpermute_b32 v250, v255, v106
	ds_bpermute_b32 v251, v255, v107
	ds_bpermute_b32 v252, v255, v108
	ds_bpermute_b32 v253, v255, v109
	v_add_f32_e32 v118, v118, v119
	v_mul_f32_e32 v119, v111, v111
	v_mul_f32_e32 v106, 0x3d372713, v98
	v_fma_f32 v106, v98, v106, 1.0
	v_mul_f32_e32 v0, v0, v106
	v_mul_f32_e32 v0, 0xbfb8aa3b, v0
	v_exp_f32_e32 v0, v0
	v_mul_f32_e32 v106, 0x3d372713, v99
	v_fma_f32 v106, v99, v106, 1.0
	v_mul_f32_e32 v120, v113, v113
	v_add_f32_e32 v0, 1.0, v0
	v_rcp_f32_e32 v0, v0
	v_fmac_f32_e32 v119, v110, v110
	v_fmac_f32_e32 v120, v112, v112
	v_add_f32_e32 v119, v119, v120
	v_mul_f32_e32 v0, v98, v0
	v_mul_f32_e32 v98, 0x3fcc422a, v99
	v_mul_f32_e32 v98, v98, v106
	v_mul_f32_e32 v98, 0xbfb8aa3b, v98
	v_exp_f32_e32 v98, v98
	v_mul_f32_e32 v106, 0x3d372713, v100
	v_fma_f32 v106, v100, v106, 1.0
	v_add_f32_e32 v118, v118, v119
	v_add_f32_e32 v98, 1.0, v98
	v_rcp_f32_e32 v98, v98
	s_nop 0
	v_mul_f32_e32 v98, v99, v98
	v_mul_f32_e32 v99, 0x3fcc422a, v100
	v_mul_f32_e32 v99, v99, v106
	v_mul_f32_e32 v99, 0xbfb8aa3b, v99
	v_exp_f32_e32 v99, v99
	v_mul_f32_e32 v106, 0x3d372713, v101
	v_fma_f32 v106, v101, v106, 1.0
	v_add_f32_e32 v99, 1.0, v99
	v_rcp_f32_e32 v99, v99
	s_nop 0
	v_mul_f32_e32 v99, v100, v99
	v_mul_f32_e32 v100, 0x3fcc422a, v101
	v_mul_f32_e32 v100, v100, v106
	v_mul_f32_e32 v100, 0xbfb8aa3b, v100
	v_exp_f32_e32 v100, v100
	v_mul_f32_e32 v106, 0x3d372713, v102
	v_fma_f32 v106, v102, v106, 1.0
	v_add_f32_e32 v100, 1.0, v100
	v_rcp_f32_e32 v100, v100
	s_nop 0
	v_mul_f32_e32 v100, v101, v100
	v_mul_f32_e32 v101, 0x3fcc422a, v102
	v_mul_f32_e32 v101, v101, v106
	v_mul_f32_e32 v101, 0xbfb8aa3b, v101
	v_exp_f32_e32 v101, v101
	v_mul_f32_e32 v106, 0x3d372713, v103
	v_fma_f32 v106, v103, v106, 1.0
	v_add_f32_e32 v101, 1.0, v101
	v_rcp_f32_e32 v101, v101
	s_nop 0
	v_mul_f32_e32 v101, v102, v101
	v_mul_f32_e32 v102, 0x3fcc422a, v103
	v_mul_f32_e32 v102, v102, v106
	v_mul_f32_e32 v102, 0xbfb8aa3b, v102
	v_exp_f32_e32 v102, v102
	v_mul_f32_e32 v106, 0x3d372713, v104
	v_fma_f32 v106, v104, v106, 1.0
	v_add_f32_e32 v102, 1.0, v102
	v_rcp_f32_e32 v102, v102
	s_nop 0
	v_mul_f32_e32 v102, v103, v102
	v_mul_f32_e32 v103, 0x3fcc422a, v104
	v_mul_f32_e32 v103, v103, v106
	v_mul_f32_e32 v103, 0xbfb8aa3b, v103
	v_exp_f32_e32 v103, v103
	v_mul_f32_e32 v106, 0x3d372713, v105
	v_fma_f32 v106, v105, v106, 1.0
	v_add_f32_e32 v103, 1.0, v103
	v_rcp_f32_e32 v103, v103
	s_nop 0
	v_mul_f32_e32 v103, v104, v103
	v_mul_f32_e32 v104, 0x3fcc422a, v105
	v_mul_f32_e32 v104, v104, v106
	v_mul_f32_e32 v104, 0xbfb8aa3b, v104
	v_exp_f32_e32 v104, v104
	v_mul_f32_e32 v106, v100, v100
	v_fmac_f32_e32 v106, v99, v99
	v_add_f32_e32 v104, 1.0, v104
	v_rcp_f32_e32 v104, v104
	s_nop 0
	v_mul_f32_e32 v104, v105, v104
	v_mul_f32_e32 v105, v98, v98
	v_fmac_f32_e32 v105, v0, v0
	v_add_f32_e32 v105, v105, v106
	v_mul_f32_e32 v106, v102, v102
	v_mul_f32_e32 v107, v104, v104
	v_fmac_f32_e32 v106, v101, v101
	v_fmac_f32_e32 v107, v103, v103
	v_add_f32_e32 v106, v106, v107
	v_add_f32_e32 v105, v105, v106
	v_add_f32_e32 v105, v118, v105
	v_cvt_pk_bf16_f32 v98, v0, v98
	v_mov_b32_e32 v0, v105
	s_nop 1
	v_permlane16_swap_b32_e32 v105, v0
	v_add_f32_e32 v0, v105, v0
	v_cvt_pk_bf16_f32 v99, v99, v100
	v_cvt_pk_bf16_f32 v100, v101, v102
	v_cvt_pk_bf16_f32 v101, v103, v104
	ds_bpermute_b32 v244, v255, v98
	ds_bpermute_b32 v245, v255, v99
	ds_bpermute_b32 v246, v255, v100
	ds_bpermute_b32 v247, v255, v101
	v_lshl_add_u64 v[248:249], v[116:117], 0, v[208:209]
	s_waitcnt lgkmcnt(4)
	global_store_dwordx4 v[248:249], v[250:253], off
	s_nop 1
	v_mov_b32_e32 v98, v0
	s_nop 1
	v_permlane32_swap_b32_e32 v0, v98
	s_and_saveexec_b64 s[0:1], s[2:3]
	s_cbranch_execz .LBB0_177
	v_add_f32_e32 v0, v0, v98
	v_lshlrev_b64 v[98:99], 7, v[114:115]
	s_lshl_b32 s36, s12, 2
	v_lshl_add_u64 v[98:99], v[138:139], 0, v[98:99]
	s_mov_b32 s37, s40
	v_lshl_add_u64 v[98:99], s[36:37], 2, v[98:99]
	s_lshl_b32 s36, s28, 2
	v_lshl_add_u64 v[98:99], v[98:99], 0, s[36:37]
	global_store_dword v[98:99], v0, off offset:-128
.LBB0_177:
	s_or_b64 exec, exec, s[0:1]
	v_add_f32_e32 v0, v173, v174
	v_fmamk_f32 v0, v0, 0x3a000000, v240
	v_rsq_f32_e32 v0, v0
	v_or_b32_e32 v98, 32, v150
	v_ashrrev_i32_e32 v99, 31, v98
	v_lshlrev_b64 v[100:101], 13, v[98:99]
	v_pk_mul_f32 v[90:91], v[90:91], v[0:1] op_sel_hi:[1,0]
	v_pk_mul_f32 v[92:93], v[92:93], v[0:1] op_sel_hi:[1,0]
	v_mul_f32_e32 v103, 0x3d372713, v90
	v_mul_f32_e32 v102, 0x3fcc422a, v90
	v_fma_f32 v103, v90, v103, 1.0
	v_mul_f32_e32 v102, v102, v103
	v_mul_f32_e32 v102, 0xbfb8aa3b, v102
	v_exp_f32_e32 v102, v102
	v_mul_f32_e32 v103, 0x3d372713, v91
	v_fma_f32 v103, v91, v103, 1.0
	v_pk_mul_f32 v[94:95], v[94:95], v[0:1] op_sel_hi:[1,0]
	v_add_f32_e32 v102, 1.0, v102
	v_rcp_f32_e32 v102, v102
	v_pk_mul_f32 v[96:97], v[96:97], v[0:1] op_sel_hi:[1,0]
	v_lshl_add_u64 v[100:101], v[152:153], 0, v[100:101]
	v_pk_mul_f32 v[82:83], v[82:83], v[0:1] op_sel_hi:[1,0]
	v_mul_f32_e32 v90, v90, v102
	v_mul_f32_e32 v102, 0x3fcc422a, v91
	v_mul_f32_e32 v102, v102, v103
	v_mul_f32_e32 v102, 0xbfb8aa3b, v102
	v_exp_f32_e32 v102, v102
	v_mul_f32_e32 v103, 0x3d372713, v92
	v_fma_f32 v103, v92, v103, 1.0
	v_pk_mul_f32 v[84:85], v[84:85], v[0:1] op_sel_hi:[1,0]
	v_add_f32_e32 v102, 1.0, v102
	v_rcp_f32_e32 v102, v102
	v_pk_mul_f32 v[88:89], v[88:89], v[0:1] op_sel_hi:[1,0]
	v_pk_mul_f32 v[86:87], v[86:87], v[0:1] op_sel_hi:[1,0]
	v_mul_f32_e32 v0, 0x3fcc422a, v82
	v_mul_f32_e32 v91, v91, v102
	v_mul_f32_e32 v102, 0x3fcc422a, v92
	v_mul_f32_e32 v102, v102, v103
	v_mul_f32_e32 v102, 0xbfb8aa3b, v102
	v_exp_f32_e32 v102, v102
	v_mul_f32_e32 v103, 0x3d372713, v93
	v_fma_f32 v103, v93, v103, 1.0
	v_add_f32_e32 v102, 1.0, v102
	v_rcp_f32_e32 v102, v102
	s_nop 0
	v_mul_f32_e32 v92, v92, v102
	v_mul_f32_e32 v102, 0x3fcc422a, v93
	v_mul_f32_e32 v102, v102, v103
	v_mul_f32_e32 v102, 0xbfb8aa3b, v102
	v_exp_f32_e32 v102, v102
	v_mul_f32_e32 v103, 0x3d372713, v94
	v_fma_f32 v103, v94, v103, 1.0
	v_add_f32_e32 v102, 1.0, v102
	v_rcp_f32_e32 v102, v102
	s_nop 0
	v_mul_f32_e32 v93, v93, v102
	v_mul_f32_e32 v102, 0x3fcc422a, v94
	v_mul_f32_e32 v102, v102, v103
	v_mul_f32_e32 v102, 0xbfb8aa3b, v102
	v_exp_f32_e32 v102, v102
	v_mul_f32_e32 v103, 0x3d372713, v95
	v_fma_f32 v103, v95, v103, 1.0
	v_add_f32_e32 v102, 1.0, v102
	v_rcp_f32_e32 v102, v102
	s_nop 0
	v_mul_f32_e32 v94, v94, v102
	v_mul_f32_e32 v102, 0x3fcc422a, v95
	v_mul_f32_e32 v102, v102, v103
	v_mul_f32_e32 v102, 0xbfb8aa3b, v102
	v_exp_f32_e32 v102, v102
	v_mul_f32_e32 v103, 0x3d372713, v96
	v_fma_f32 v103, v96, v103, 1.0
	v_add_f32_e32 v102, 1.0, v102
	v_rcp_f32_e32 v102, v102
	s_nop 0
	v_mul_f32_e32 v95, v95, v102
	v_mul_f32_e32 v102, 0x3fcc422a, v96
	v_mul_f32_e32 v102, v102, v103
	v_mul_f32_e32 v102, 0xbfb8aa3b, v102
	v_exp_f32_e32 v102, v102
	v_mul_f32_e32 v103, 0x3d372713, v97
	v_fma_f32 v103, v97, v103, 1.0
	v_add_f32_e32 v102, 1.0, v102
	v_rcp_f32_e32 v102, v102
	s_nop 0
	v_mul_f32_e32 v96, v96, v102
	v_mul_f32_e32 v102, 0x3fcc422a, v97
	v_mul_f32_e32 v102, v102, v103
	v_mul_f32_e32 v102, 0xbfb8aa3b, v102
	v_exp_f32_e32 v102, v102
	v_mul_f32_e32 v103, v93, v93
	v_fmac_f32_e32 v103, v92, v92
	v_add_f32_e32 v102, 1.0, v102
	v_rcp_f32_e32 v102, v102
	s_nop 0
	v_mul_f32_e32 v97, v97, v102
	v_mul_f32_e32 v102, v91, v91
	v_fmac_f32_e32 v102, v90, v90
	v_cvt_pk_bf16_f32 v90, v90, v91
	v_cvt_pk_bf16_f32 v91, v92, v93
	v_cvt_pk_bf16_f32 v92, v94, v95
	v_cvt_pk_bf16_f32 v93, v96, v97
	s_waitcnt lgkmcnt(0)
	global_store_dwordx4 v[248:249], v[244:247], off offset:256
	ds_bpermute_b32 v250, v255, v90
	ds_bpermute_b32 v251, v255, v91
	ds_bpermute_b32 v252, v255, v92
	ds_bpermute_b32 v253, v255, v93
	v_add_f32_e32 v102, v102, v103
	v_mul_f32_e32 v103, v95, v95
	v_mul_f32_e32 v90, 0x3d372713, v82
	v_fma_f32 v90, v82, v90, 1.0
	v_mul_f32_e32 v0, v0, v90
	v_mul_f32_e32 v0, 0xbfb8aa3b, v0
	v_exp_f32_e32 v0, v0
	v_mul_f32_e32 v90, 0x3d372713, v83
	v_fma_f32 v90, v83, v90, 1.0
	v_mul_f32_e32 v104, v97, v97
	v_add_f32_e32 v0, 1.0, v0
	v_rcp_f32_e32 v0, v0
	v_fmac_f32_e32 v103, v94, v94
	v_fmac_f32_e32 v104, v96, v96
	v_add_f32_e32 v103, v103, v104
	v_mul_f32_e32 v0, v82, v0
	v_mul_f32_e32 v82, 0x3fcc422a, v83
	v_mul_f32_e32 v82, v82, v90
	v_mul_f32_e32 v82, 0xbfb8aa3b, v82
	v_exp_f32_e32 v82, v82
	v_mul_f32_e32 v90, 0x3d372713, v84
	v_fma_f32 v90, v84, v90, 1.0
	v_add_f32_e32 v102, v102, v103
	v_add_f32_e32 v82, 1.0, v82
	v_rcp_f32_e32 v82, v82
	s_nop 0
	v_mul_f32_e32 v82, v83, v82
	v_mul_f32_e32 v83, 0x3fcc422a, v84
	v_mul_f32_e32 v83, v83, v90
	v_mul_f32_e32 v83, 0xbfb8aa3b, v83
	v_exp_f32_e32 v83, v83
	v_mul_f32_e32 v90, 0x3d372713, v85
	v_fma_f32 v90, v85, v90, 1.0
	v_add_f32_e32 v83, 1.0, v83
	v_rcp_f32_e32 v83, v83
	s_nop 0
	v_mul_f32_e32 v83, v84, v83
	v_mul_f32_e32 v84, 0x3fcc422a, v85
	v_mul_f32_e32 v84, v84, v90
	v_mul_f32_e32 v84, 0xbfb8aa3b, v84
	v_exp_f32_e32 v84, v84
	v_mul_f32_e32 v90, 0x3d372713, v86
	v_fma_f32 v90, v86, v90, 1.0
	v_add_f32_e32 v84, 1.0, v84
	v_rcp_f32_e32 v84, v84
	s_nop 0
	v_mul_f32_e32 v84, v85, v84
	v_mul_f32_e32 v85, 0x3fcc422a, v86
	v_mul_f32_e32 v85, v85, v90
	v_mul_f32_e32 v85, 0xbfb8aa3b, v85
	v_exp_f32_e32 v85, v85
	v_mul_f32_e32 v90, 0x3d372713, v87
	v_fma_f32 v90, v87, v90, 1.0
	v_add_f32_e32 v85, 1.0, v85
	v_rcp_f32_e32 v85, v85
	s_nop 0
	v_mul_f32_e32 v85, v86, v85
	v_mul_f32_e32 v86, 0x3fcc422a, v87
	v_mul_f32_e32 v86, v86, v90
	v_mul_f32_e32 v86, 0xbfb8aa3b, v86
	v_exp_f32_e32 v86, v86
	v_mul_f32_e32 v90, 0x3d372713, v88
	v_fma_f32 v90, v88, v90, 1.0
	v_add_f32_e32 v86, 1.0, v86
	v_rcp_f32_e32 v86, v86
	s_nop 0
	v_mul_f32_e32 v86, v87, v86
	v_mul_f32_e32 v87, 0x3fcc422a, v88
	v_mul_f32_e32 v87, v87, v90
	v_mul_f32_e32 v87, 0xbfb8aa3b, v87
	v_exp_f32_e32 v87, v87
	v_mul_f32_e32 v90, 0x3d372713, v89
	v_fma_f32 v90, v89, v90, 1.0
	v_add_f32_e32 v87, 1.0, v87
	v_rcp_f32_e32 v87, v87
	s_nop 0
	v_mul_f32_e32 v87, v88, v87
	v_mul_f32_e32 v88, 0x3fcc422a, v89
	v_mul_f32_e32 v88, v88, v90
	v_mul_f32_e32 v88, 0xbfb8aa3b, v88
	v_exp_f32_e32 v88, v88
	v_mul_f32_e32 v90, v84, v84
	v_fmac_f32_e32 v90, v83, v83
	v_add_f32_e32 v88, 1.0, v88
	v_rcp_f32_e32 v88, v88
	s_nop 0
	v_mul_f32_e32 v88, v89, v88
	v_mul_f32_e32 v89, v82, v82
	v_fmac_f32_e32 v89, v0, v0
	v_add_f32_e32 v89, v89, v90
	v_mul_f32_e32 v90, v86, v86
	v_mul_f32_e32 v91, v88, v88
	v_fmac_f32_e32 v90, v85, v85
	v_fmac_f32_e32 v91, v87, v87
	v_add_f32_e32 v90, v90, v91
	v_add_f32_e32 v89, v89, v90
	v_add_f32_e32 v89, v102, v89
	v_cvt_pk_bf16_f32 v82, v0, v82
	v_mov_b32_e32 v0, v89
	s_nop 1
	v_permlane16_swap_b32_e32 v89, v0
	v_add_f32_e32 v0, v89, v0
	v_cvt_pk_bf16_f32 v83, v83, v84
	v_cvt_pk_bf16_f32 v84, v85, v86
	v_cvt_pk_bf16_f32 v85, v87, v88
	ds_bpermute_b32 v244, v255, v82
	ds_bpermute_b32 v245, v255, v83
	ds_bpermute_b32 v246, v255, v84
	ds_bpermute_b32 v247, v255, v85
	v_lshl_add_u64 v[248:249], v[100:101], 0, v[208:209]
	s_waitcnt lgkmcnt(4)
	global_store_dwordx4 v[248:249], v[250:253], off
	s_nop 1
	v_mov_b32_e32 v82, v0
	s_nop 1
	v_permlane32_swap_b32_e32 v0, v82
	s_and_saveexec_b64 s[0:1], s[2:3]
	s_cbranch_execz .LBB0_179
	v_add_f32_e32 v0, v0, v82
	v_lshlrev_b64 v[82:83], 7, v[98:99]
	s_lshl_b32 s36, s12, 2
	v_lshl_add_u64 v[82:83], v[138:139], 0, v[82:83]
	s_mov_b32 s37, s40
	v_lshl_add_u64 v[82:83], s[36:37], 2, v[82:83]
	s_lshl_b32 s36, s28, 2
	v_lshl_add_u64 v[82:83], v[82:83], 0, s[36:37]
	global_store_dword v[82:83], v0, off offset:-128
.LBB0_179:
	s_or_b64 exec, exec, s[0:1]
	v_add_f32_e32 v0, v171, v172
	v_fmamk_f32 v0, v0, 0x3a000000, v240
	v_rsq_f32_e32 v0, v0
	v_or_b32_e32 v82, 48, v150
	v_ashrrev_i32_e32 v83, 31, v82
	v_lshlrev_b64 v[84:85], 13, v[82:83]
	v_pk_mul_f32 v[74:75], v[74:75], v[0:1] op_sel_hi:[1,0]
	v_pk_mul_f32 v[76:77], v[76:77], v[0:1] op_sel_hi:[1,0]
	v_mul_f32_e32 v87, 0x3d372713, v74
	v_mul_f32_e32 v86, 0x3fcc422a, v74
	v_fma_f32 v87, v74, v87, 1.0
	v_mul_f32_e32 v86, v86, v87
	v_mul_f32_e32 v86, 0xbfb8aa3b, v86
	v_exp_f32_e32 v86, v86
	v_mul_f32_e32 v87, 0x3d372713, v75
	v_fma_f32 v87, v75, v87, 1.0
	v_pk_mul_f32 v[78:79], v[78:79], v[0:1] op_sel_hi:[1,0]
	v_add_f32_e32 v86, 1.0, v86
	v_rcp_f32_e32 v86, v86
	v_pk_mul_f32 v[80:81], v[80:81], v[0:1] op_sel_hi:[1,0]
	v_lshl_add_u64 v[84:85], v[152:153], 0, v[84:85]
	v_pk_mul_f32 v[66:67], v[66:67], v[0:1] op_sel_hi:[1,0]
	v_mul_f32_e32 v74, v74, v86
	v_mul_f32_e32 v86, 0x3fcc422a, v75
	v_mul_f32_e32 v86, v86, v87
	v_mul_f32_e32 v86, 0xbfb8aa3b, v86
	v_exp_f32_e32 v86, v86
	v_mul_f32_e32 v87, 0x3d372713, v76
	v_fma_f32 v87, v76, v87, 1.0
	v_pk_mul_f32 v[68:69], v[68:69], v[0:1] op_sel_hi:[1,0]
	v_add_f32_e32 v86, 1.0, v86
	v_rcp_f32_e32 v86, v86
	v_pk_mul_f32 v[72:73], v[72:73], v[0:1] op_sel_hi:[1,0]
	v_pk_mul_f32 v[70:71], v[70:71], v[0:1] op_sel_hi:[1,0]
	v_mul_f32_e32 v0, 0x3fcc422a, v66
	v_mul_f32_e32 v75, v75, v86
	v_mul_f32_e32 v86, 0x3fcc422a, v76
	v_mul_f32_e32 v86, v86, v87
	v_mul_f32_e32 v86, 0xbfb8aa3b, v86
	v_exp_f32_e32 v86, v86
	v_mul_f32_e32 v87, 0x3d372713, v77
	v_fma_f32 v87, v77, v87, 1.0
	v_add_f32_e32 v86, 1.0, v86
	v_rcp_f32_e32 v86, v86
	s_nop 0
	v_mul_f32_e32 v76, v76, v86
	v_mul_f32_e32 v86, 0x3fcc422a, v77
	v_mul_f32_e32 v86, v86, v87
	v_mul_f32_e32 v86, 0xbfb8aa3b, v86
	v_exp_f32_e32 v86, v86
	v_mul_f32_e32 v87, 0x3d372713, v78
	v_fma_f32 v87, v78, v87, 1.0
	v_add_f32_e32 v86, 1.0, v86
	v_rcp_f32_e32 v86, v86
	s_nop 0
	v_mul_f32_e32 v77, v77, v86
	v_mul_f32_e32 v86, 0x3fcc422a, v78
	v_mul_f32_e32 v86, v86, v87
	v_mul_f32_e32 v86, 0xbfb8aa3b, v86
	v_exp_f32_e32 v86, v86
	v_mul_f32_e32 v87, 0x3d372713, v79
	v_fma_f32 v87, v79, v87, 1.0
	v_add_f32_e32 v86, 1.0, v86
	v_rcp_f32_e32 v86, v86
	s_nop 0
	v_mul_f32_e32 v78, v78, v86
	v_mul_f32_e32 v86, 0x3fcc422a, v79
	v_mul_f32_e32 v86, v86, v87
	v_mul_f32_e32 v86, 0xbfb8aa3b, v86
	v_exp_f32_e32 v86, v86
	v_mul_f32_e32 v87, 0x3d372713, v80
	v_fma_f32 v87, v80, v87, 1.0
	v_add_f32_e32 v86, 1.0, v86
	v_rcp_f32_e32 v86, v86
	s_nop 0
	v_mul_f32_e32 v79, v79, v86
	v_mul_f32_e32 v86, 0x3fcc422a, v80
	v_mul_f32_e32 v86, v86, v87
	v_mul_f32_e32 v86, 0xbfb8aa3b, v86
	v_exp_f32_e32 v86, v86
	v_mul_f32_e32 v87, 0x3d372713, v81
	v_fma_f32 v87, v81, v87, 1.0
	v_add_f32_e32 v86, 1.0, v86
	v_rcp_f32_e32 v86, v86
	s_nop 0
	v_mul_f32_e32 v80, v80, v86
	v_mul_f32_e32 v86, 0x3fcc422a, v81
	v_mul_f32_e32 v86, v86, v87
	v_mul_f32_e32 v86, 0xbfb8aa3b, v86
	v_exp_f32_e32 v86, v86
	v_mul_f32_e32 v87, v77, v77
	v_fmac_f32_e32 v87, v76, v76
	v_add_f32_e32 v86, 1.0, v86
	v_rcp_f32_e32 v86, v86
	s_nop 0
	v_mul_f32_e32 v81, v81, v86
	v_mul_f32_e32 v86, v75, v75
	v_fmac_f32_e32 v86, v74, v74
	v_cvt_pk_bf16_f32 v74, v74, v75
	v_cvt_pk_bf16_f32 v75, v76, v77
	v_cvt_pk_bf16_f32 v76, v78, v79
	v_cvt_pk_bf16_f32 v77, v80, v81
	s_waitcnt lgkmcnt(0)
	global_store_dwordx4 v[248:249], v[244:247], off offset:256
	ds_bpermute_b32 v250, v255, v74
	ds_bpermute_b32 v251, v255, v75
	ds_bpermute_b32 v252, v255, v76
	ds_bpermute_b32 v253, v255, v77
	v_add_f32_e32 v86, v86, v87
	v_mul_f32_e32 v87, v79, v79
	v_mul_f32_e32 v74, 0x3d372713, v66
	v_fma_f32 v74, v66, v74, 1.0
	v_mul_f32_e32 v0, v0, v74
	v_mul_f32_e32 v0, 0xbfb8aa3b, v0
	v_exp_f32_e32 v0, v0
	v_mul_f32_e32 v74, 0x3d372713, v67
	v_fma_f32 v74, v67, v74, 1.0
	v_mul_f32_e32 v88, v81, v81
	v_add_f32_e32 v0, 1.0, v0
	v_rcp_f32_e32 v0, v0
	v_fmac_f32_e32 v87, v78, v78
	v_fmac_f32_e32 v88, v80, v80
	v_add_f32_e32 v87, v87, v88
	v_mul_f32_e32 v0, v66, v0
	v_mul_f32_e32 v66, 0x3fcc422a, v67
	v_mul_f32_e32 v66, v66, v74
	v_mul_f32_e32 v66, 0xbfb8aa3b, v66
	v_exp_f32_e32 v66, v66
	v_mul_f32_e32 v74, 0x3d372713, v68
	v_fma_f32 v74, v68, v74, 1.0
	v_add_f32_e32 v86, v86, v87
	v_add_f32_e32 v66, 1.0, v66
	v_rcp_f32_e32 v66, v66
	s_nop 0
	v_mul_f32_e32 v66, v67, v66
	v_mul_f32_e32 v67, 0x3fcc422a, v68
	v_mul_f32_e32 v67, v67, v74
	v_mul_f32_e32 v67, 0xbfb8aa3b, v67
	v_exp_f32_e32 v67, v67
	v_mul_f32_e32 v74, 0x3d372713, v69
	v_fma_f32 v74, v69, v74, 1.0
	v_add_f32_e32 v67, 1.0, v67
	v_rcp_f32_e32 v67, v67
	s_nop 0
	v_mul_f32_e32 v67, v68, v67
	v_mul_f32_e32 v68, 0x3fcc422a, v69
	v_mul_f32_e32 v68, v68, v74
	v_mul_f32_e32 v68, 0xbfb8aa3b, v68
	v_exp_f32_e32 v68, v68
	v_mul_f32_e32 v74, 0x3d372713, v70
	v_fma_f32 v74, v70, v74, 1.0
	v_add_f32_e32 v68, 1.0, v68
	v_rcp_f32_e32 v68, v68
	s_nop 0
	v_mul_f32_e32 v68, v69, v68
	v_mul_f32_e32 v69, 0x3fcc422a, v70
	v_mul_f32_e32 v69, v69, v74
	v_mul_f32_e32 v69, 0xbfb8aa3b, v69
	v_exp_f32_e32 v69, v69
	v_mul_f32_e32 v74, 0x3d372713, v71
	v_fma_f32 v74, v71, v74, 1.0
	v_add_f32_e32 v69, 1.0, v69
	v_rcp_f32_e32 v69, v69
	s_nop 0
	v_mul_f32_e32 v69, v70, v69
	v_mul_f32_e32 v70, 0x3fcc422a, v71
	v_mul_f32_e32 v70, v70, v74
	v_mul_f32_e32 v70, 0xbfb8aa3b, v70
	v_exp_f32_e32 v70, v70
	v_mul_f32_e32 v74, 0x3d372713, v72
	v_fma_f32 v74, v72, v74, 1.0
	v_add_f32_e32 v70, 1.0, v70
	v_rcp_f32_e32 v70, v70
	s_nop 0
	v_mul_f32_e32 v70, v71, v70
	v_mul_f32_e32 v71, 0x3fcc422a, v72
	v_mul_f32_e32 v71, v71, v74
	v_mul_f32_e32 v71, 0xbfb8aa3b, v71
	v_exp_f32_e32 v71, v71
	v_mul_f32_e32 v74, 0x3d372713, v73
	v_fma_f32 v74, v73, v74, 1.0
	v_add_f32_e32 v71, 1.0, v71
	v_rcp_f32_e32 v71, v71
	s_nop 0
	v_mul_f32_e32 v71, v72, v71
	v_mul_f32_e32 v72, 0x3fcc422a, v73
	v_mul_f32_e32 v72, v72, v74
	v_mul_f32_e32 v72, 0xbfb8aa3b, v72
	v_exp_f32_e32 v72, v72
	v_mul_f32_e32 v74, v68, v68
	v_fmac_f32_e32 v74, v67, v67
	v_add_f32_e32 v72, 1.0, v72
	v_rcp_f32_e32 v72, v72
	s_nop 0
	v_mul_f32_e32 v72, v73, v72
	v_mul_f32_e32 v73, v66, v66
	v_fmac_f32_e32 v73, v0, v0
	v_add_f32_e32 v73, v73, v74
	v_mul_f32_e32 v74, v70, v70
	v_mul_f32_e32 v75, v72, v72
	v_fmac_f32_e32 v74, v69, v69
	v_fmac_f32_e32 v75, v71, v71
	v_add_f32_e32 v74, v74, v75
	v_add_f32_e32 v73, v73, v74
	v_add_f32_e32 v73, v86, v73
	v_cvt_pk_bf16_f32 v66, v0, v66
	v_mov_b32_e32 v0, v73
	s_nop 1
	v_permlane16_swap_b32_e32 v73, v0
	v_add_f32_e32 v0, v73, v0
	v_cvt_pk_bf16_f32 v67, v67, v68
	v_cvt_pk_bf16_f32 v68, v69, v70
	v_cvt_pk_bf16_f32 v69, v71, v72
	ds_bpermute_b32 v244, v255, v66
	ds_bpermute_b32 v245, v255, v67
	ds_bpermute_b32 v246, v255, v68
	ds_bpermute_b32 v247, v255, v69
	v_lshl_add_u64 v[248:249], v[84:85], 0, v[208:209]
	s_waitcnt lgkmcnt(4)
	global_store_dwordx4 v[248:249], v[250:253], off
	s_nop 1
	v_mov_b32_e32 v66, v0
	s_nop 1
	v_permlane32_swap_b32_e32 v0, v66
	s_and_saveexec_b64 s[0:1], s[2:3]
	s_cbranch_execz .LBB0_181
	v_add_f32_e32 v0, v0, v66
	v_lshlrev_b64 v[66:67], 7, v[82:83]
	s_lshl_b32 s36, s12, 2
	v_lshl_add_u64 v[66:67], v[138:139], 0, v[66:67]
	s_mov_b32 s37, s40
	v_lshl_add_u64 v[66:67], s[36:37], 2, v[66:67]
	s_lshl_b32 s36, s28, 2
	v_lshl_add_u64 v[66:67], v[66:67], 0, s[36:37]
	global_store_dword v[66:67], v0, off offset:-128
.LBB0_181:
	s_or_b64 exec, exec, s[0:1]
	v_add_f32_e32 v0, v169, v170
	v_fmamk_f32 v0, v0, 0x3a000000, v240
	v_rsq_f32_e32 v0, v0
	v_add_u32_e32 v66, 0x80, v150
	v_ashrrev_i32_e32 v67, 31, v66
	v_lshlrev_b64 v[68:69], 13, v[66:67]
	v_pk_mul_f32 v[58:59], v[58:59], v[0:1] op_sel_hi:[1,0]
	v_pk_mul_f32 v[60:61], v[60:61], v[0:1] op_sel_hi:[1,0]
	v_mul_f32_e32 v71, 0x3d372713, v58
	v_mul_f32_e32 v70, 0x3fcc422a, v58
	v_fma_f32 v71, v58, v71, 1.0
	v_mul_f32_e32 v70, v70, v71
	v_mul_f32_e32 v70, 0xbfb8aa3b, v70
	v_exp_f32_e32 v70, v70
	v_mul_f32_e32 v71, 0x3d372713, v59
	v_fma_f32 v71, v59, v71, 1.0
	v_pk_mul_f32 v[62:63], v[62:63], v[0:1] op_sel_hi:[1,0]
	v_add_f32_e32 v70, 1.0, v70
	v_rcp_f32_e32 v70, v70
	v_pk_mul_f32 v[64:65], v[64:65], v[0:1] op_sel_hi:[1,0]
	v_lshl_add_u64 v[68:69], v[152:153], 0, v[68:69]
	v_pk_mul_f32 v[50:51], v[50:51], v[0:1] op_sel_hi:[1,0]
	v_mul_f32_e32 v58, v58, v70
	v_mul_f32_e32 v70, 0x3fcc422a, v59
	v_mul_f32_e32 v70, v70, v71
	v_mul_f32_e32 v70, 0xbfb8aa3b, v70
	v_exp_f32_e32 v70, v70
	v_mul_f32_e32 v71, 0x3d372713, v60
	v_fma_f32 v71, v60, v71, 1.0
	v_pk_mul_f32 v[52:53], v[52:53], v[0:1] op_sel_hi:[1,0]
	v_add_f32_e32 v70, 1.0, v70
	v_rcp_f32_e32 v70, v70
	v_pk_mul_f32 v[56:57], v[56:57], v[0:1] op_sel_hi:[1,0]
	v_pk_mul_f32 v[54:55], v[54:55], v[0:1] op_sel_hi:[1,0]
	v_mul_f32_e32 v0, 0x3fcc422a, v50
	v_mul_f32_e32 v59, v59, v70
	v_mul_f32_e32 v70, 0x3fcc422a, v60
	v_mul_f32_e32 v70, v70, v71
	v_mul_f32_e32 v70, 0xbfb8aa3b, v70
	v_exp_f32_e32 v70, v70
	v_mul_f32_e32 v71, 0x3d372713, v61
	v_fma_f32 v71, v61, v71, 1.0
	v_add_f32_e32 v70, 1.0, v70
	v_rcp_f32_e32 v70, v70
	s_nop 0
	v_mul_f32_e32 v60, v60, v70
	v_mul_f32_e32 v70, 0x3fcc422a, v61
	v_mul_f32_e32 v70, v70, v71
	v_mul_f32_e32 v70, 0xbfb8aa3b, v70
	v_exp_f32_e32 v70, v70
	v_mul_f32_e32 v71, 0x3d372713, v62
	v_fma_f32 v71, v62, v71, 1.0
	v_add_f32_e32 v70, 1.0, v70
	v_rcp_f32_e32 v70, v70
	s_nop 0
	v_mul_f32_e32 v61, v61, v70
	v_mul_f32_e32 v70, 0x3fcc422a, v62
	v_mul_f32_e32 v70, v70, v71
	v_mul_f32_e32 v70, 0xbfb8aa3b, v70
	v_exp_f32_e32 v70, v70
	v_mul_f32_e32 v71, 0x3d372713, v63
	v_fma_f32 v71, v63, v71, 1.0
	v_add_f32_e32 v70, 1.0, v70
	v_rcp_f32_e32 v70, v70
	s_nop 0
	v_mul_f32_e32 v62, v62, v70
	v_mul_f32_e32 v70, 0x3fcc422a, v63
	v_mul_f32_e32 v70, v70, v71
	v_mul_f32_e32 v70, 0xbfb8aa3b, v70
	v_exp_f32_e32 v70, v70
	v_mul_f32_e32 v71, 0x3d372713, v64
	v_fma_f32 v71, v64, v71, 1.0
	v_add_f32_e32 v70, 1.0, v70
	v_rcp_f32_e32 v70, v70
	s_nop 0
	v_mul_f32_e32 v63, v63, v70
	v_mul_f32_e32 v70, 0x3fcc422a, v64
	v_mul_f32_e32 v70, v70, v71
	v_mul_f32_e32 v70, 0xbfb8aa3b, v70
	v_exp_f32_e32 v70, v70
	v_mul_f32_e32 v71, 0x3d372713, v65
	v_fma_f32 v71, v65, v71, 1.0
	v_add_f32_e32 v70, 1.0, v70
	v_rcp_f32_e32 v70, v70
	s_nop 0
	v_mul_f32_e32 v64, v64, v70
	v_mul_f32_e32 v70, 0x3fcc422a, v65
	v_mul_f32_e32 v70, v70, v71
	v_mul_f32_e32 v70, 0xbfb8aa3b, v70
	v_exp_f32_e32 v70, v70
	v_mul_f32_e32 v71, v61, v61
	v_fmac_f32_e32 v71, v60, v60
	v_add_f32_e32 v70, 1.0, v70
	v_rcp_f32_e32 v70, v70
	s_nop 0
	v_mul_f32_e32 v65, v65, v70
	v_mul_f32_e32 v70, v59, v59
	v_fmac_f32_e32 v70, v58, v58
	v_cvt_pk_bf16_f32 v58, v58, v59
	v_cvt_pk_bf16_f32 v59, v60, v61
	v_cvt_pk_bf16_f32 v60, v62, v63
	v_cvt_pk_bf16_f32 v61, v64, v65
	s_waitcnt lgkmcnt(0)
	global_store_dwordx4 v[248:249], v[244:247], off offset:256
	ds_bpermute_b32 v250, v255, v58
	ds_bpermute_b32 v251, v255, v59
	ds_bpermute_b32 v252, v255, v60
	ds_bpermute_b32 v253, v255, v61
	v_add_f32_e32 v70, v70, v71
	v_mul_f32_e32 v71, v63, v63
	v_mul_f32_e32 v58, 0x3d372713, v50
	v_fma_f32 v58, v50, v58, 1.0
	v_mul_f32_e32 v0, v0, v58
	v_mul_f32_e32 v0, 0xbfb8aa3b, v0
	v_exp_f32_e32 v0, v0
	v_mul_f32_e32 v58, 0x3d372713, v51
	v_fma_f32 v58, v51, v58, 1.0
	v_mul_f32_e32 v72, v65, v65
	v_add_f32_e32 v0, 1.0, v0
	v_rcp_f32_e32 v0, v0
	v_fmac_f32_e32 v71, v62, v62
	v_fmac_f32_e32 v72, v64, v64
	v_add_f32_e32 v71, v71, v72
	v_mul_f32_e32 v0, v50, v0
	v_mul_f32_e32 v50, 0x3fcc422a, v51
	v_mul_f32_e32 v50, v50, v58
	v_mul_f32_e32 v50, 0xbfb8aa3b, v50
	v_exp_f32_e32 v50, v50
	v_mul_f32_e32 v58, 0x3d372713, v52
	v_fma_f32 v58, v52, v58, 1.0
	v_add_f32_e32 v70, v70, v71
	v_add_f32_e32 v50, 1.0, v50
	v_rcp_f32_e32 v50, v50
	s_nop 0
	v_mul_f32_e32 v50, v51, v50
	v_mul_f32_e32 v51, 0x3fcc422a, v52
	v_mul_f32_e32 v51, v51, v58
	v_mul_f32_e32 v51, 0xbfb8aa3b, v51
	v_exp_f32_e32 v51, v51
	v_mul_f32_e32 v58, 0x3d372713, v53
	v_fma_f32 v58, v53, v58, 1.0
	v_add_f32_e32 v51, 1.0, v51
	v_rcp_f32_e32 v51, v51
	s_nop 0
	v_mul_f32_e32 v51, v52, v51
	v_mul_f32_e32 v52, 0x3fcc422a, v53
	v_mul_f32_e32 v52, v52, v58
	v_mul_f32_e32 v52, 0xbfb8aa3b, v52
	v_exp_f32_e32 v52, v52
	v_mul_f32_e32 v58, 0x3d372713, v54
	v_fma_f32 v58, v54, v58, 1.0
	v_add_f32_e32 v52, 1.0, v52
	v_rcp_f32_e32 v52, v52
	s_nop 0
	v_mul_f32_e32 v52, v53, v52
	v_mul_f32_e32 v53, 0x3fcc422a, v54
	v_mul_f32_e32 v53, v53, v58
	v_mul_f32_e32 v53, 0xbfb8aa3b, v53
	v_exp_f32_e32 v53, v53
	v_mul_f32_e32 v58, 0x3d372713, v55
	v_fma_f32 v58, v55, v58, 1.0
	v_add_f32_e32 v53, 1.0, v53
	v_rcp_f32_e32 v53, v53
	s_nop 0
	v_mul_f32_e32 v53, v54, v53
	v_mul_f32_e32 v54, 0x3fcc422a, v55
	v_mul_f32_e32 v54, v54, v58
	v_mul_f32_e32 v54, 0xbfb8aa3b, v54
	v_exp_f32_e32 v54, v54
	v_mul_f32_e32 v58, 0x3d372713, v56
	v_fma_f32 v58, v56, v58, 1.0
	v_add_f32_e32 v54, 1.0, v54
	v_rcp_f32_e32 v54, v54
	s_nop 0
	v_mul_f32_e32 v54, v55, v54
	v_mul_f32_e32 v55, 0x3fcc422a, v56
	v_mul_f32_e32 v55, v55, v58
	v_mul_f32_e32 v55, 0xbfb8aa3b, v55
	v_exp_f32_e32 v55, v55
	v_mul_f32_e32 v58, 0x3d372713, v57
	v_fma_f32 v58, v57, v58, 1.0
	v_add_f32_e32 v55, 1.0, v55
	v_rcp_f32_e32 v55, v55
	s_nop 0
	v_mul_f32_e32 v55, v56, v55
	v_mul_f32_e32 v56, 0x3fcc422a, v57
	v_mul_f32_e32 v56, v56, v58
	v_mul_f32_e32 v56, 0xbfb8aa3b, v56
	v_exp_f32_e32 v56, v56
	v_mul_f32_e32 v58, v52, v52
	v_fmac_f32_e32 v58, v51, v51
	v_add_f32_e32 v56, 1.0, v56
	v_rcp_f32_e32 v56, v56
	s_nop 0
	v_mul_f32_e32 v56, v57, v56
	v_mul_f32_e32 v57, v50, v50
	v_fmac_f32_e32 v57, v0, v0
	v_add_f32_e32 v57, v57, v58
	v_mul_f32_e32 v58, v54, v54
	v_mul_f32_e32 v59, v56, v56
	v_fmac_f32_e32 v58, v53, v53
	v_fmac_f32_e32 v59, v55, v55
	v_add_f32_e32 v58, v58, v59
	v_add_f32_e32 v57, v57, v58
	v_add_f32_e32 v57, v70, v57
	v_cvt_pk_bf16_f32 v50, v0, v50
	v_mov_b32_e32 v0, v57
	s_nop 1
	v_permlane16_swap_b32_e32 v57, v0
	v_add_f32_e32 v0, v57, v0
	v_cvt_pk_bf16_f32 v51, v51, v52
	v_cvt_pk_bf16_f32 v52, v53, v54
	v_cvt_pk_bf16_f32 v53, v55, v56
	ds_bpermute_b32 v244, v255, v50
	ds_bpermute_b32 v245, v255, v51
	ds_bpermute_b32 v246, v255, v52
	ds_bpermute_b32 v247, v255, v53
	v_lshl_add_u64 v[248:249], v[68:69], 0, v[208:209]
	s_waitcnt lgkmcnt(4)
	global_store_dwordx4 v[248:249], v[250:253], off
	s_nop 1
	v_mov_b32_e32 v50, v0
	s_nop 1
	v_permlane32_swap_b32_e32 v0, v50
	s_and_saveexec_b64 s[0:1], s[2:3]
	s_cbranch_execz .LBB0_183
	v_add_f32_e32 v0, v0, v50
	v_lshlrev_b64 v[50:51], 7, v[66:67]
	s_lshl_b32 s36, s12, 2
	v_lshl_add_u64 v[50:51], v[138:139], 0, v[50:51]
	s_mov_b32 s37, s40
	v_lshl_add_u64 v[50:51], s[36:37], 2, v[50:51]
	s_lshl_b32 s36, s28, 2
	v_lshl_add_u64 v[50:51], v[50:51], 0, s[36:37]
	global_store_dword v[50:51], v0, off offset:-128
.LBB0_183:
	s_or_b64 exec, exec, s[0:1]
	v_add_f32_e32 v0, v161, v168
	v_fmamk_f32 v0, v0, 0x3a000000, v240
	v_rsq_f32_e32 v0, v0
	v_add_u32_e32 v50, 0x90, v150
	v_ashrrev_i32_e32 v51, 31, v50
	v_lshlrev_b64 v[52:53], 13, v[50:51]
	v_pk_mul_f32 v[42:43], v[42:43], v[0:1] op_sel_hi:[1,0]
	v_pk_mul_f32 v[44:45], v[44:45], v[0:1] op_sel_hi:[1,0]
	v_mul_f32_e32 v55, 0x3d372713, v42
	v_mul_f32_e32 v54, 0x3fcc422a, v42
	v_fma_f32 v55, v42, v55, 1.0
	v_mul_f32_e32 v54, v54, v55
	v_mul_f32_e32 v54, 0xbfb8aa3b, v54
	v_exp_f32_e32 v54, v54
	v_mul_f32_e32 v55, 0x3d372713, v43
	v_fma_f32 v55, v43, v55, 1.0
	v_pk_mul_f32 v[46:47], v[46:47], v[0:1] op_sel_hi:[1,0]
	v_add_f32_e32 v54, 1.0, v54
	v_rcp_f32_e32 v54, v54
	v_pk_mul_f32 v[48:49], v[48:49], v[0:1] op_sel_hi:[1,0]
	v_lshl_add_u64 v[52:53], v[152:153], 0, v[52:53]
	v_pk_mul_f32 v[34:35], v[34:35], v[0:1] op_sel_hi:[1,0]
	v_mul_f32_e32 v42, v42, v54
	v_mul_f32_e32 v54, 0x3fcc422a, v43
	v_mul_f32_e32 v54, v54, v55
	v_mul_f32_e32 v54, 0xbfb8aa3b, v54
	v_exp_f32_e32 v54, v54
	v_mul_f32_e32 v55, 0x3d372713, v44
	v_fma_f32 v55, v44, v55, 1.0
	v_pk_mul_f32 v[36:37], v[36:37], v[0:1] op_sel_hi:[1,0]
	v_add_f32_e32 v54, 1.0, v54
	v_rcp_f32_e32 v54, v54
	v_pk_mul_f32 v[40:41], v[40:41], v[0:1] op_sel_hi:[1,0]
	v_pk_mul_f32 v[38:39], v[38:39], v[0:1] op_sel_hi:[1,0]
	v_mul_f32_e32 v0, 0x3fcc422a, v34
	v_mul_f32_e32 v43, v43, v54
	v_mul_f32_e32 v54, 0x3fcc422a, v44
	v_mul_f32_e32 v54, v54, v55
	v_mul_f32_e32 v54, 0xbfb8aa3b, v54
	v_exp_f32_e32 v54, v54
	v_mul_f32_e32 v55, 0x3d372713, v45
	v_fma_f32 v55, v45, v55, 1.0
	v_add_f32_e32 v54, 1.0, v54
	v_rcp_f32_e32 v54, v54
	s_nop 0
	v_mul_f32_e32 v44, v44, v54
	v_mul_f32_e32 v54, 0x3fcc422a, v45
	v_mul_f32_e32 v54, v54, v55
	v_mul_f32_e32 v54, 0xbfb8aa3b, v54
	v_exp_f32_e32 v54, v54
	v_mul_f32_e32 v55, 0x3d372713, v46
	v_fma_f32 v55, v46, v55, 1.0
	v_add_f32_e32 v54, 1.0, v54
	v_rcp_f32_e32 v54, v54
	s_nop 0
	v_mul_f32_e32 v45, v45, v54
	v_mul_f32_e32 v54, 0x3fcc422a, v46
	v_mul_f32_e32 v54, v54, v55
	v_mul_f32_e32 v54, 0xbfb8aa3b, v54
	v_exp_f32_e32 v54, v54
	v_mul_f32_e32 v55, 0x3d372713, v47
	v_fma_f32 v55, v47, v55, 1.0
	v_add_f32_e32 v54, 1.0, v54
	v_rcp_f32_e32 v54, v54
	s_nop 0
	v_mul_f32_e32 v46, v46, v54
	v_mul_f32_e32 v54, 0x3fcc422a, v47
	v_mul_f32_e32 v54, v54, v55
	v_mul_f32_e32 v54, 0xbfb8aa3b, v54
	v_exp_f32_e32 v54, v54
	v_mul_f32_e32 v55, 0x3d372713, v48
	v_fma_f32 v55, v48, v55, 1.0
	v_add_f32_e32 v54, 1.0, v54
	v_rcp_f32_e32 v54, v54
	s_nop 0
	v_mul_f32_e32 v47, v47, v54
	v_mul_f32_e32 v54, 0x3fcc422a, v48
	v_mul_f32_e32 v54, v54, v55
	v_mul_f32_e32 v54, 0xbfb8aa3b, v54
	v_exp_f32_e32 v54, v54
	v_mul_f32_e32 v55, 0x3d372713, v49
	v_fma_f32 v55, v49, v55, 1.0
	v_add_f32_e32 v54, 1.0, v54
	v_rcp_f32_e32 v54, v54
	s_nop 0
	v_mul_f32_e32 v48, v48, v54
	v_mul_f32_e32 v54, 0x3fcc422a, v49
	v_mul_f32_e32 v54, v54, v55
	v_mul_f32_e32 v54, 0xbfb8aa3b, v54
	v_exp_f32_e32 v54, v54
	v_mul_f32_e32 v55, v45, v45
	v_fmac_f32_e32 v55, v44, v44
	v_add_f32_e32 v54, 1.0, v54
	v_rcp_f32_e32 v54, v54
	s_nop 0
	v_mul_f32_e32 v49, v49, v54
	v_mul_f32_e32 v54, v43, v43
	v_fmac_f32_e32 v54, v42, v42
	v_cvt_pk_bf16_f32 v42, v42, v43
	v_cvt_pk_bf16_f32 v43, v44, v45
	v_cvt_pk_bf16_f32 v44, v46, v47
	v_cvt_pk_bf16_f32 v45, v48, v49
	s_waitcnt lgkmcnt(0)
	global_store_dwordx4 v[248:249], v[244:247], off offset:256
	ds_bpermute_b32 v250, v255, v42
	ds_bpermute_b32 v251, v255, v43
	ds_bpermute_b32 v252, v255, v44
	ds_bpermute_b32 v253, v255, v45
	v_add_f32_e32 v54, v54, v55
	v_mul_f32_e32 v55, v47, v47
	v_mul_f32_e32 v42, 0x3d372713, v34
	v_fma_f32 v42, v34, v42, 1.0
	v_mul_f32_e32 v0, v0, v42
	v_mul_f32_e32 v0, 0xbfb8aa3b, v0
	v_exp_f32_e32 v0, v0
	v_mul_f32_e32 v42, 0x3d372713, v35
	v_fma_f32 v42, v35, v42, 1.0
	v_mul_f32_e32 v56, v49, v49
	v_add_f32_e32 v0, 1.0, v0
	v_rcp_f32_e32 v0, v0
	v_fmac_f32_e32 v55, v46, v46
	v_fmac_f32_e32 v56, v48, v48
	v_add_f32_e32 v55, v55, v56
	v_mul_f32_e32 v0, v34, v0
	v_mul_f32_e32 v34, 0x3fcc422a, v35
	v_mul_f32_e32 v34, v34, v42
	v_mul_f32_e32 v34, 0xbfb8aa3b, v34
	v_exp_f32_e32 v34, v34
	v_mul_f32_e32 v42, 0x3d372713, v36
	v_fma_f32 v42, v36, v42, 1.0
	v_add_f32_e32 v54, v54, v55
	v_add_f32_e32 v34, 1.0, v34
	v_rcp_f32_e32 v34, v34
	s_nop 0
	v_mul_f32_e32 v34, v35, v34
	v_mul_f32_e32 v35, 0x3fcc422a, v36
	v_mul_f32_e32 v35, v35, v42
	v_mul_f32_e32 v35, 0xbfb8aa3b, v35
	v_exp_f32_e32 v35, v35
	v_mul_f32_e32 v42, 0x3d372713, v37
	v_fma_f32 v42, v37, v42, 1.0
	v_add_f32_e32 v35, 1.0, v35
	v_rcp_f32_e32 v35, v35
	s_nop 0
	v_mul_f32_e32 v35, v36, v35
	v_mul_f32_e32 v36, 0x3fcc422a, v37
	v_mul_f32_e32 v36, v36, v42
	v_mul_f32_e32 v36, 0xbfb8aa3b, v36
	v_exp_f32_e32 v36, v36
	v_mul_f32_e32 v42, 0x3d372713, v38
	v_fma_f32 v42, v38, v42, 1.0
	v_add_f32_e32 v36, 1.0, v36
	v_rcp_f32_e32 v36, v36
	s_nop 0
	v_mul_f32_e32 v36, v37, v36
	v_mul_f32_e32 v37, 0x3fcc422a, v38
	v_mul_f32_e32 v37, v37, v42
	v_mul_f32_e32 v37, 0xbfb8aa3b, v37
	v_exp_f32_e32 v37, v37
	v_mul_f32_e32 v42, 0x3d372713, v39
	v_fma_f32 v42, v39, v42, 1.0
	v_add_f32_e32 v37, 1.0, v37
	v_rcp_f32_e32 v37, v37
	s_nop 0
	v_mul_f32_e32 v37, v38, v37
	v_mul_f32_e32 v38, 0x3fcc422a, v39
	v_mul_f32_e32 v38, v38, v42
	v_mul_f32_e32 v38, 0xbfb8aa3b, v38
	v_exp_f32_e32 v38, v38
	v_mul_f32_e32 v42, 0x3d372713, v40
	v_fma_f32 v42, v40, v42, 1.0
	v_add_f32_e32 v38, 1.0, v38
	v_rcp_f32_e32 v38, v38
	s_nop 0
	v_mul_f32_e32 v38, v39, v38
	v_mul_f32_e32 v39, 0x3fcc422a, v40
	v_mul_f32_e32 v39, v39, v42
	v_mul_f32_e32 v39, 0xbfb8aa3b, v39
	v_exp_f32_e32 v39, v39
	v_mul_f32_e32 v42, 0x3d372713, v41
	v_fma_f32 v42, v41, v42, 1.0
	v_add_f32_e32 v39, 1.0, v39
	v_rcp_f32_e32 v39, v39
	s_nop 0
	v_mul_f32_e32 v39, v40, v39
	v_mul_f32_e32 v40, 0x3fcc422a, v41
	v_mul_f32_e32 v40, v40, v42
	v_mul_f32_e32 v40, 0xbfb8aa3b, v40
	v_exp_f32_e32 v40, v40
	v_mul_f32_e32 v42, v36, v36
	v_fmac_f32_e32 v42, v35, v35
	v_add_f32_e32 v40, 1.0, v40
	v_rcp_f32_e32 v40, v40
	s_nop 0
	v_mul_f32_e32 v40, v41, v40
	v_mul_f32_e32 v41, v34, v34
	v_fmac_f32_e32 v41, v0, v0
	v_add_f32_e32 v41, v41, v42
	v_mul_f32_e32 v42, v38, v38
	v_mul_f32_e32 v43, v40, v40
	v_fmac_f32_e32 v42, v37, v37
	v_fmac_f32_e32 v43, v39, v39
	v_add_f32_e32 v42, v42, v43
	v_add_f32_e32 v41, v41, v42
	v_add_f32_e32 v41, v54, v41
	v_cvt_pk_bf16_f32 v34, v0, v34
	v_mov_b32_e32 v0, v41
	s_nop 1
	v_permlane16_swap_b32_e32 v41, v0
	v_add_f32_e32 v0, v41, v0
	v_cvt_pk_bf16_f32 v35, v35, v36
	v_cvt_pk_bf16_f32 v36, v37, v38
	v_cvt_pk_bf16_f32 v37, v39, v40
	ds_bpermute_b32 v244, v255, v34
	ds_bpermute_b32 v245, v255, v35
	ds_bpermute_b32 v246, v255, v36
	ds_bpermute_b32 v247, v255, v37
	v_lshl_add_u64 v[248:249], v[52:53], 0, v[208:209]
	s_waitcnt lgkmcnt(4)
	global_store_dwordx4 v[248:249], v[250:253], off
	s_nop 1
	v_mov_b32_e32 v34, v0
	s_nop 1
	v_permlane32_swap_b32_e32 v0, v34
	s_and_saveexec_b64 s[0:1], s[2:3]
	s_cbranch_execz .LBB0_185
	v_add_f32_e32 v0, v0, v34
	v_lshlrev_b64 v[34:35], 7, v[50:51]
	s_lshl_b32 s36, s12, 2
	v_lshl_add_u64 v[34:35], v[138:139], 0, v[34:35]
	s_mov_b32 s37, s40
	v_lshl_add_u64 v[34:35], s[36:37], 2, v[34:35]
	s_lshl_b32 s36, s28, 2
	v_lshl_add_u64 v[34:35], v[34:35], 0, s[36:37]
	global_store_dword v[34:35], v0, off offset:-128
.LBB0_185:
	s_or_b64 exec, exec, s[0:1]
	v_add_f32_e32 v0, v159, v160
	v_fmamk_f32 v0, v0, 0x3a000000, v240
	v_rsq_f32_e32 v0, v0
	v_add_u32_e32 v34, 0xa0, v150
	v_ashrrev_i32_e32 v35, 31, v34
	v_lshlrev_b64 v[36:37], 13, v[34:35]
	v_pk_mul_f32 v[26:27], v[26:27], v[0:1] op_sel_hi:[1,0]
	v_pk_mul_f32 v[28:29], v[28:29], v[0:1] op_sel_hi:[1,0]
	v_mul_f32_e32 v39, 0x3d372713, v26
	v_mul_f32_e32 v38, 0x3fcc422a, v26
	v_fma_f32 v39, v26, v39, 1.0
	v_mul_f32_e32 v38, v38, v39
	v_mul_f32_e32 v38, 0xbfb8aa3b, v38
	v_exp_f32_e32 v38, v38
	v_mul_f32_e32 v39, 0x3d372713, v27
	v_fma_f32 v39, v27, v39, 1.0
	v_pk_mul_f32 v[30:31], v[30:31], v[0:1] op_sel_hi:[1,0]
	v_add_f32_e32 v38, 1.0, v38
	v_rcp_f32_e32 v38, v38
	v_pk_mul_f32 v[32:33], v[32:33], v[0:1] op_sel_hi:[1,0]
	v_lshl_add_u64 v[36:37], v[152:153], 0, v[36:37]
	v_pk_mul_f32 v[18:19], v[18:19], v[0:1] op_sel_hi:[1,0]
	v_mul_f32_e32 v26, v26, v38
	v_mul_f32_e32 v38, 0x3fcc422a, v27
	v_mul_f32_e32 v38, v38, v39
	v_mul_f32_e32 v38, 0xbfb8aa3b, v38
	v_exp_f32_e32 v38, v38
	v_mul_f32_e32 v39, 0x3d372713, v28
	v_fma_f32 v39, v28, v39, 1.0
	v_pk_mul_f32 v[20:21], v[20:21], v[0:1] op_sel_hi:[1,0]
	v_add_f32_e32 v38, 1.0, v38
	v_rcp_f32_e32 v38, v38
	v_pk_mul_f32 v[24:25], v[24:25], v[0:1] op_sel_hi:[1,0]
	v_pk_mul_f32 v[22:23], v[22:23], v[0:1] op_sel_hi:[1,0]
	v_mul_f32_e32 v0, 0x3fcc422a, v18
	v_mul_f32_e32 v27, v27, v38
	v_mul_f32_e32 v38, 0x3fcc422a, v28
	v_mul_f32_e32 v38, v38, v39
	v_mul_f32_e32 v38, 0xbfb8aa3b, v38
	v_exp_f32_e32 v38, v38
	v_mul_f32_e32 v39, 0x3d372713, v29
	v_fma_f32 v39, v29, v39, 1.0
	v_add_f32_e32 v38, 1.0, v38
	v_rcp_f32_e32 v38, v38
	s_nop 0
	v_mul_f32_e32 v28, v28, v38
	v_mul_f32_e32 v38, 0x3fcc422a, v29
	v_mul_f32_e32 v38, v38, v39
	v_mul_f32_e32 v38, 0xbfb8aa3b, v38
	v_exp_f32_e32 v38, v38
	v_mul_f32_e32 v39, 0x3d372713, v30
	v_fma_f32 v39, v30, v39, 1.0
	v_add_f32_e32 v38, 1.0, v38
	v_rcp_f32_e32 v38, v38
	s_nop 0
	v_mul_f32_e32 v29, v29, v38
	v_mul_f32_e32 v38, 0x3fcc422a, v30
	v_mul_f32_e32 v38, v38, v39
	v_mul_f32_e32 v38, 0xbfb8aa3b, v38
	v_exp_f32_e32 v38, v38
	v_mul_f32_e32 v39, 0x3d372713, v31
	v_fma_f32 v39, v31, v39, 1.0
	v_add_f32_e32 v38, 1.0, v38
	v_rcp_f32_e32 v38, v38
	s_nop 0
	v_mul_f32_e32 v30, v30, v38
	v_mul_f32_e32 v38, 0x3fcc422a, v31
	v_mul_f32_e32 v38, v38, v39
	v_mul_f32_e32 v38, 0xbfb8aa3b, v38
	v_exp_f32_e32 v38, v38
	v_mul_f32_e32 v39, 0x3d372713, v32
	v_fma_f32 v39, v32, v39, 1.0
	v_add_f32_e32 v38, 1.0, v38
	v_rcp_f32_e32 v38, v38
	s_nop 0
	v_mul_f32_e32 v31, v31, v38
	v_mul_f32_e32 v38, 0x3fcc422a, v32
	v_mul_f32_e32 v38, v38, v39
	v_mul_f32_e32 v38, 0xbfb8aa3b, v38
	v_exp_f32_e32 v38, v38
	v_mul_f32_e32 v39, 0x3d372713, v33
	v_fma_f32 v39, v33, v39, 1.0
	v_add_f32_e32 v38, 1.0, v38
	v_rcp_f32_e32 v38, v38
	s_nop 0
	v_mul_f32_e32 v32, v32, v38
	v_mul_f32_e32 v38, 0x3fcc422a, v33
	v_mul_f32_e32 v38, v38, v39
	v_mul_f32_e32 v38, 0xbfb8aa3b, v38
	v_exp_f32_e32 v38, v38
	v_mul_f32_e32 v39, v29, v29
	v_fmac_f32_e32 v39, v28, v28
	v_add_f32_e32 v38, 1.0, v38
	v_rcp_f32_e32 v38, v38
	s_nop 0
	v_mul_f32_e32 v33, v33, v38
	v_mul_f32_e32 v38, v27, v27
	v_fmac_f32_e32 v38, v26, v26
	v_cvt_pk_bf16_f32 v26, v26, v27
	v_cvt_pk_bf16_f32 v27, v28, v29
	v_cvt_pk_bf16_f32 v28, v30, v31
	v_cvt_pk_bf16_f32 v29, v32, v33
	s_waitcnt lgkmcnt(0)
	global_store_dwordx4 v[248:249], v[244:247], off offset:256
	ds_bpermute_b32 v250, v255, v26
	ds_bpermute_b32 v251, v255, v27
	ds_bpermute_b32 v252, v255, v28
	ds_bpermute_b32 v253, v255, v29
	v_add_f32_e32 v38, v38, v39
	v_mul_f32_e32 v39, v31, v31
	v_mul_f32_e32 v26, 0x3d372713, v18
	v_fma_f32 v26, v18, v26, 1.0
	v_mul_f32_e32 v0, v0, v26
	v_mul_f32_e32 v0, 0xbfb8aa3b, v0
	v_exp_f32_e32 v0, v0
	v_mul_f32_e32 v26, 0x3d372713, v19
	v_fma_f32 v26, v19, v26, 1.0
	v_mul_f32_e32 v40, v33, v33
	v_add_f32_e32 v0, 1.0, v0
	v_rcp_f32_e32 v0, v0
	v_fmac_f32_e32 v39, v30, v30
	v_fmac_f32_e32 v40, v32, v32
	v_add_f32_e32 v39, v39, v40
	v_mul_f32_e32 v0, v18, v0
	v_mul_f32_e32 v18, 0x3fcc422a, v19
	v_mul_f32_e32 v18, v18, v26
	v_mul_f32_e32 v18, 0xbfb8aa3b, v18
	v_exp_f32_e32 v18, v18
	v_mul_f32_e32 v26, 0x3d372713, v20
	v_fma_f32 v26, v20, v26, 1.0
	v_add_f32_e32 v38, v38, v39
	v_add_f32_e32 v18, 1.0, v18
	v_rcp_f32_e32 v18, v18
	s_nop 0
	v_mul_f32_e32 v18, v19, v18
	v_mul_f32_e32 v19, 0x3fcc422a, v20
	v_mul_f32_e32 v19, v19, v26
	v_mul_f32_e32 v19, 0xbfb8aa3b, v19
	v_exp_f32_e32 v19, v19
	v_mul_f32_e32 v26, 0x3d372713, v21
	v_fma_f32 v26, v21, v26, 1.0
	v_add_f32_e32 v19, 1.0, v19
	v_rcp_f32_e32 v19, v19
	s_nop 0
	v_mul_f32_e32 v19, v20, v19
	v_mul_f32_e32 v20, 0x3fcc422a, v21
	v_mul_f32_e32 v20, v20, v26
	v_mul_f32_e32 v20, 0xbfb8aa3b, v20
	v_exp_f32_e32 v20, v20
	v_mul_f32_e32 v26, 0x3d372713, v22
	v_fma_f32 v26, v22, v26, 1.0
	v_add_f32_e32 v20, 1.0, v20
	v_rcp_f32_e32 v20, v20
	s_nop 0
	v_mul_f32_e32 v20, v21, v20
	v_mul_f32_e32 v21, 0x3fcc422a, v22
	v_mul_f32_e32 v21, v21, v26
	v_mul_f32_e32 v21, 0xbfb8aa3b, v21
	v_exp_f32_e32 v21, v21
	v_mul_f32_e32 v26, 0x3d372713, v23
	v_fma_f32 v26, v23, v26, 1.0
	v_add_f32_e32 v21, 1.0, v21
	v_rcp_f32_e32 v21, v21
	s_nop 0
	v_mul_f32_e32 v21, v22, v21
	v_mul_f32_e32 v22, 0x3fcc422a, v23
	v_mul_f32_e32 v22, v22, v26
	v_mul_f32_e32 v22, 0xbfb8aa3b, v22
	v_exp_f32_e32 v22, v22
	v_mul_f32_e32 v26, 0x3d372713, v24
	v_fma_f32 v26, v24, v26, 1.0
	v_add_f32_e32 v22, 1.0, v22
	v_rcp_f32_e32 v22, v22
	s_nop 0
	v_mul_f32_e32 v22, v23, v22
	v_mul_f32_e32 v23, 0x3fcc422a, v24
	v_mul_f32_e32 v23, v23, v26
	v_mul_f32_e32 v23, 0xbfb8aa3b, v23
	v_exp_f32_e32 v23, v23
	v_mul_f32_e32 v26, 0x3d372713, v25
	v_fma_f32 v26, v25, v26, 1.0
	v_add_f32_e32 v23, 1.0, v23
	v_rcp_f32_e32 v23, v23
	s_nop 0
	v_mul_f32_e32 v23, v24, v23
	v_mul_f32_e32 v24, 0x3fcc422a, v25
	v_mul_f32_e32 v24, v24, v26
	v_mul_f32_e32 v24, 0xbfb8aa3b, v24
	v_exp_f32_e32 v24, v24
	v_mul_f32_e32 v26, v20, v20
	v_fmac_f32_e32 v26, v19, v19
	v_add_f32_e32 v24, 1.0, v24
	v_rcp_f32_e32 v24, v24
	s_nop 0
	v_mul_f32_e32 v24, v25, v24
	v_mul_f32_e32 v25, v18, v18
	v_fmac_f32_e32 v25, v0, v0
	v_add_f32_e32 v25, v25, v26
	v_mul_f32_e32 v26, v22, v22
	v_mul_f32_e32 v27, v24, v24
	v_fmac_f32_e32 v26, v21, v21
	v_fmac_f32_e32 v27, v23, v23
	v_add_f32_e32 v26, v26, v27
	v_add_f32_e32 v25, v25, v26
	v_add_f32_e32 v25, v38, v25
	v_cvt_pk_bf16_f32 v18, v0, v18
	v_mov_b32_e32 v0, v25
	s_nop 1
	v_permlane16_swap_b32_e32 v25, v0
	v_add_f32_e32 v0, v25, v0
	v_cvt_pk_bf16_f32 v19, v19, v20
	v_cvt_pk_bf16_f32 v20, v21, v22
	v_cvt_pk_bf16_f32 v21, v23, v24
	ds_bpermute_b32 v244, v255, v18
	ds_bpermute_b32 v245, v255, v19
	ds_bpermute_b32 v246, v255, v20
	ds_bpermute_b32 v247, v255, v21
	v_lshl_add_u64 v[248:249], v[36:37], 0, v[208:209]
	s_waitcnt lgkmcnt(4)
	global_store_dwordx4 v[248:249], v[250:253], off
	s_nop 1
	v_mov_b32_e32 v18, v0
	s_nop 1
	v_permlane32_swap_b32_e32 v0, v18
	s_and_saveexec_b64 s[0:1], s[2:3]
	s_cbranch_execz .LBB0_187
	v_add_f32_e32 v0, v0, v18
	v_lshlrev_b64 v[18:19], 7, v[34:35]
	s_lshl_b32 s36, s12, 2
	v_lshl_add_u64 v[18:19], v[138:139], 0, v[18:19]
	s_mov_b32 s37, s40
	v_lshl_add_u64 v[18:19], s[36:37], 2, v[18:19]
	s_lshl_b32 s36, s28, 2
	v_lshl_add_u64 v[18:19], v[18:19], 0, s[36:37]
	global_store_dword v[18:19], v0, off offset:-128
.LBB0_187:
	s_or_b64 exec, exec, s[0:1]
	v_add_f32_e32 v0, v157, v158
	v_fmamk_f32 v0, v0, 0x3a000000, v240
	v_rsq_f32_e32 v0, v0
	v_add_u32_e32 v18, 0xb0, v150
	v_ashrrev_i32_e32 v19, 31, v18
	v_lshlrev_b64 v[20:21], 13, v[18:19]
	v_pk_mul_f32 v[10:11], v[10:11], v[0:1] op_sel_hi:[1,0]
	v_pk_mul_f32 v[12:13], v[12:13], v[0:1] op_sel_hi:[1,0]
	v_mul_f32_e32 v23, 0x3d372713, v10
	v_mul_f32_e32 v22, 0x3fcc422a, v10
	v_fma_f32 v23, v10, v23, 1.0
	v_mul_f32_e32 v22, v22, v23
	v_mul_f32_e32 v22, 0xbfb8aa3b, v22
	v_exp_f32_e32 v22, v22
	v_mul_f32_e32 v23, 0x3d372713, v11
	v_fma_f32 v23, v11, v23, 1.0
	v_pk_mul_f32 v[14:15], v[14:15], v[0:1] op_sel_hi:[1,0]
	v_add_f32_e32 v22, 1.0, v22
	v_rcp_f32_e32 v22, v22
	v_pk_mul_f32 v[16:17], v[16:17], v[0:1] op_sel_hi:[1,0]
	v_lshl_add_u64 v[20:21], v[152:153], 0, v[20:21]
	v_pk_mul_f32 v[2:3], v[2:3], v[0:1] op_sel_hi:[1,0]
	v_mul_f32_e32 v10, v10, v22
	v_mul_f32_e32 v22, 0x3fcc422a, v11
	v_mul_f32_e32 v22, v22, v23
	v_mul_f32_e32 v22, 0xbfb8aa3b, v22
	v_exp_f32_e32 v22, v22
	v_mul_f32_e32 v23, 0x3d372713, v12
	v_fma_f32 v23, v12, v23, 1.0
	v_pk_mul_f32 v[4:5], v[4:5], v[0:1] op_sel_hi:[1,0]
	v_add_f32_e32 v22, 1.0, v22
	v_rcp_f32_e32 v22, v22
	v_pk_mul_f32 v[8:9], v[8:9], v[0:1] op_sel_hi:[1,0]
	v_pk_mul_f32 v[6:7], v[6:7], v[0:1] op_sel_hi:[1,0]
	v_mul_f32_e32 v0, 0x3fcc422a, v2
	v_mul_f32_e32 v11, v11, v22
	v_mul_f32_e32 v22, 0x3fcc422a, v12
	v_mul_f32_e32 v22, v22, v23
	v_mul_f32_e32 v22, 0xbfb8aa3b, v22
	v_exp_f32_e32 v22, v22
	v_mul_f32_e32 v23, 0x3d372713, v13
	v_fma_f32 v23, v13, v23, 1.0
	v_add_f32_e32 v22, 1.0, v22
	v_rcp_f32_e32 v22, v22
	s_nop 0
	v_mul_f32_e32 v12, v12, v22
	v_mul_f32_e32 v22, 0x3fcc422a, v13
	v_mul_f32_e32 v22, v22, v23
	v_mul_f32_e32 v22, 0xbfb8aa3b, v22
	v_exp_f32_e32 v22, v22
	v_mul_f32_e32 v23, 0x3d372713, v14
	v_fma_f32 v23, v14, v23, 1.0
	v_add_f32_e32 v22, 1.0, v22
	v_rcp_f32_e32 v22, v22
	s_nop 0
	v_mul_f32_e32 v13, v13, v22
	v_mul_f32_e32 v22, 0x3fcc422a, v14
	v_mul_f32_e32 v22, v22, v23
	v_mul_f32_e32 v22, 0xbfb8aa3b, v22
	v_exp_f32_e32 v22, v22
	v_mul_f32_e32 v23, 0x3d372713, v15
	v_fma_f32 v23, v15, v23, 1.0
	v_add_f32_e32 v22, 1.0, v22
	v_rcp_f32_e32 v22, v22
	s_nop 0
	v_mul_f32_e32 v14, v14, v22
	v_mul_f32_e32 v22, 0x3fcc422a, v15
	v_mul_f32_e32 v22, v22, v23
	v_mul_f32_e32 v22, 0xbfb8aa3b, v22
	v_exp_f32_e32 v22, v22
	v_mul_f32_e32 v23, 0x3d372713, v16
	v_fma_f32 v23, v16, v23, 1.0
	v_add_f32_e32 v22, 1.0, v22
	v_rcp_f32_e32 v22, v22
	s_nop 0
	v_mul_f32_e32 v15, v15, v22
	v_mul_f32_e32 v22, 0x3fcc422a, v16
	v_mul_f32_e32 v22, v22, v23
	v_mul_f32_e32 v22, 0xbfb8aa3b, v22
	v_exp_f32_e32 v22, v22
	v_mul_f32_e32 v23, 0x3d372713, v17
	v_fma_f32 v23, v17, v23, 1.0
	v_add_f32_e32 v22, 1.0, v22
	v_rcp_f32_e32 v22, v22
	s_nop 0
	v_mul_f32_e32 v16, v16, v22
	v_mul_f32_e32 v22, 0x3fcc422a, v17
	v_mul_f32_e32 v22, v22, v23
	v_mul_f32_e32 v22, 0xbfb8aa3b, v22
	v_exp_f32_e32 v22, v22
	v_mul_f32_e32 v23, v13, v13
	v_fmac_f32_e32 v23, v12, v12
	v_add_f32_e32 v22, 1.0, v22
	v_rcp_f32_e32 v22, v22
	s_nop 0
	v_mul_f32_e32 v17, v17, v22
	v_mul_f32_e32 v22, v11, v11
	v_fmac_f32_e32 v22, v10, v10
	v_cvt_pk_bf16_f32 v10, v10, v11
	v_cvt_pk_bf16_f32 v11, v12, v13
	v_cvt_pk_bf16_f32 v12, v14, v15
	v_cvt_pk_bf16_f32 v13, v16, v17
	s_waitcnt lgkmcnt(0)
	global_store_dwordx4 v[248:249], v[244:247], off offset:256
	ds_bpermute_b32 v250, v255, v10
	ds_bpermute_b32 v251, v255, v11
	ds_bpermute_b32 v252, v255, v12
	ds_bpermute_b32 v253, v255, v13
	v_add_f32_e32 v22, v22, v23
	v_mul_f32_e32 v23, v15, v15
	v_mul_f32_e32 v10, 0x3d372713, v2
	v_fma_f32 v10, v2, v10, 1.0
	v_mul_f32_e32 v0, v0, v10
	v_mul_f32_e32 v0, 0xbfb8aa3b, v0
	v_exp_f32_e32 v0, v0
	v_mul_f32_e32 v10, 0x3d372713, v3
	v_fma_f32 v10, v3, v10, 1.0
	v_mul_f32_e32 v24, v17, v17
	v_add_f32_e32 v0, 1.0, v0
	v_rcp_f32_e32 v0, v0
	v_fmac_f32_e32 v23, v14, v14
	v_fmac_f32_e32 v24, v16, v16
	v_add_f32_e32 v23, v23, v24
	v_mul_f32_e32 v0, v2, v0
	v_mul_f32_e32 v2, 0x3fcc422a, v3
	v_mul_f32_e32 v2, v2, v10
	v_mul_f32_e32 v2, 0xbfb8aa3b, v2
	v_exp_f32_e32 v2, v2
	v_mul_f32_e32 v10, 0x3d372713, v4
	v_fma_f32 v10, v4, v10, 1.0
	v_add_f32_e32 v22, v22, v23
	v_add_f32_e32 v2, 1.0, v2
	v_rcp_f32_e32 v2, v2
	s_nop 0
	v_mul_f32_e32 v2, v3, v2
	v_mul_f32_e32 v3, 0x3fcc422a, v4
	v_mul_f32_e32 v3, v3, v10
	v_mul_f32_e32 v3, 0xbfb8aa3b, v3
	v_exp_f32_e32 v3, v3
	v_mul_f32_e32 v10, 0x3d372713, v5
	v_fma_f32 v10, v5, v10, 1.0
	v_add_f32_e32 v3, 1.0, v3
	v_rcp_f32_e32 v3, v3
	s_nop 0
	v_mul_f32_e32 v3, v4, v3
	v_mul_f32_e32 v4, 0x3fcc422a, v5
	v_mul_f32_e32 v4, v4, v10
	v_mul_f32_e32 v4, 0xbfb8aa3b, v4
	v_exp_f32_e32 v4, v4
	v_mul_f32_e32 v10, 0x3d372713, v6
	v_fma_f32 v10, v6, v10, 1.0
	v_add_f32_e32 v4, 1.0, v4
	v_rcp_f32_e32 v4, v4
	s_nop 0
	v_mul_f32_e32 v4, v5, v4
	v_mul_f32_e32 v5, 0x3fcc422a, v6
	v_mul_f32_e32 v5, v5, v10
	v_mul_f32_e32 v5, 0xbfb8aa3b, v5
	v_exp_f32_e32 v5, v5
	v_mul_f32_e32 v10, 0x3d372713, v7
	v_fma_f32 v10, v7, v10, 1.0
	v_add_f32_e32 v5, 1.0, v5
	v_rcp_f32_e32 v5, v5
	s_nop 0
	v_mul_f32_e32 v5, v6, v5
	v_mul_f32_e32 v6, 0x3fcc422a, v7
	v_mul_f32_e32 v6, v6, v10
	v_mul_f32_e32 v6, 0xbfb8aa3b, v6
	v_exp_f32_e32 v6, v6
	v_mul_f32_e32 v10, 0x3d372713, v8
	v_fma_f32 v10, v8, v10, 1.0
	v_add_f32_e32 v6, 1.0, v6
	v_rcp_f32_e32 v6, v6
	s_nop 0
	v_mul_f32_e32 v6, v7, v6
	v_mul_f32_e32 v7, 0x3fcc422a, v8
	v_mul_f32_e32 v7, v7, v10
	v_mul_f32_e32 v7, 0xbfb8aa3b, v7
	v_exp_f32_e32 v7, v7
	v_mul_f32_e32 v10, 0x3d372713, v9
	v_fma_f32 v10, v9, v10, 1.0
	v_add_f32_e32 v7, 1.0, v7
	v_rcp_f32_e32 v7, v7
	s_nop 0
	v_mul_f32_e32 v7, v8, v7
	v_mul_f32_e32 v8, 0x3fcc422a, v9
	v_mul_f32_e32 v8, v8, v10
	v_mul_f32_e32 v8, 0xbfb8aa3b, v8
	v_exp_f32_e32 v8, v8
	v_mul_f32_e32 v10, v4, v4
	v_fmac_f32_e32 v10, v3, v3
	v_add_f32_e32 v8, 1.0, v8
	v_rcp_f32_e32 v8, v8
	s_nop 0
	v_mul_f32_e32 v8, v9, v8
	v_mul_f32_e32 v9, v2, v2
	v_fmac_f32_e32 v9, v0, v0
	v_add_f32_e32 v9, v9, v10
	v_mul_f32_e32 v10, v6, v6
	v_mul_f32_e32 v11, v8, v8
	v_fmac_f32_e32 v10, v5, v5
	v_fmac_f32_e32 v11, v7, v7
	v_add_f32_e32 v10, v10, v11
	v_add_f32_e32 v9, v9, v10
	v_add_f32_e32 v9, v22, v9
	v_cvt_pk_bf16_f32 v2, v0, v2
	v_mov_b32_e32 v0, v9
	s_nop 1
	v_permlane16_swap_b32_e32 v9, v0
	v_add_f32_e32 v0, v9, v0
	v_cvt_pk_bf16_f32 v3, v3, v4
	v_cvt_pk_bf16_f32 v4, v5, v6
	v_cvt_pk_bf16_f32 v5, v7, v8
	ds_bpermute_b32 v244, v255, v2
	ds_bpermute_b32 v245, v255, v3
	ds_bpermute_b32 v246, v255, v4
	ds_bpermute_b32 v247, v255, v5
	v_lshl_add_u64 v[248:249], v[20:21], 0, v[208:209]
	s_waitcnt lgkmcnt(4)
	global_store_dwordx4 v[248:249], v[250:253], off
	s_waitcnt lgkmcnt(0)
	global_store_dwordx4 v[248:249], v[244:247], off offset:256
	s_nop 1
	v_mov_b32_e32 v2, v0
	s_nop 1
	v_permlane32_swap_b32_e32 v0, v2
	s_and_saveexec_b64 s[0:1], s[2:3]
	s_cbranch_execz .LBB0_189
	v_add_f32_e32 v0, v0, v2
	v_lshlrev_b64 v[2:3], 7, v[18:19]
	s_lshl_b32 s2, s12, 2
	v_lshl_add_u64 v[2:3], v[138:139], 0, v[2:3]
	s_mov_b32 s3, s40
	v_lshl_add_u64 v[2:3], s[2:3], 2, v[2:3]
	s_lshl_b32 s2, s28, 2
	v_lshl_add_u64 v[2:3], v[2:3], 0, s[2:3]
	global_store_dword v[2:3], v0, off offset:-128

.LBB0_238:
	s_or_b64 exec, exec, s[0:1]
	s_waitcnt lgkmcnt(0)
	s_barrier
	v_mov_b32_e32 v244, 0xbab64f3b
	v_not_b32_e32 v245, 31
	v_mov_b32_e32 v246, 0x7fc00000
	v_mov_b32_e32 v247, 0x7f800000
	v_mov_b32_e32 v248, 0xff61b1e6
	v_mov_b32_e32 v249, 0x3c0881c4
.LBB0_239:
	v_readlane_b32 s2, v254, 2
	v_readlane_b32 s3, v254, 3
	s_cmp_ge_i32 s41, s2
	s_cselect_b64 s[0:1], -1, 0
	s_cmp_lt_i32 s41, s3
	s_cselect_b64 s[2:3], -1, 0
	s_and_b64 s[2:3], s[0:1], s[2:3]
	s_mov_b64 s[0:1], -1
	s_and_b64 vcc, exec, s[2:3]
	s_cbranch_vccnz .LBB0_241
	v_readlane_b32 s0, v254, 10
	s_add_i32 s41, s0, 2
	s_mov_b64 s[0:1], 0

.Lalign_skip_1:
	v_mov_b32_e32 v151, v150
	s_nop 1
	v_permlane16_swap_b32_e32 v150, v151
	v_add_f32_e32 v161, v150, v151
	v_lshlrev_b32_e32 v150, 16, v176
	v_and_b32_e32 v151, 0xffff0000, v176
	v_add_f32_e32 v150, v150, v151
	v_lshlrev_b32_e32 v151, 16, v177
	v_and_b32_e32 v154, 0xffff0000, v177
	v_add_f32_e32 v151, v151, v154
	v_add_f32_e32 v150, v150, v151
	v_lshlrev_b32_e32 v151, 16, v178
	v_and_b32_e32 v154, 0xffff0000, v178
	v_add_f32_e32 v151, v151, v154
	v_lshlrev_b32_e32 v154, 16, v179
	v_and_b32_e32 v155, 0xffff0000, v179
	v_add_f32_e32 v154, v154, v155
	ds_read_b128 v[176:179], v167 offset:10240
	ds_read_b128 v[180:183], v167 offset:11264
	v_add_f32_e32 v151, v151, v154
	v_add_f32_e32 v150, v150, v151
	v_mov_b32_e32 v151, v150
	s_nop 1
	v_permlane16_swap_b32_e32 v150, v151
	v_add_f32_e32 v159, v150, v151
	s_waitcnt lgkmcnt(0)
	v_lshlrev_b32_e32 v150, 16, v176
	v_and_b32_e32 v151, 0xffff0000, v176
	v_add_f32_e32 v150, v150, v151
	v_lshlrev_b32_e32 v151, 16, v177
	v_and_b32_e32 v154, 0xffff0000, v177
	v_add_f32_e32 v151, v151, v154
	v_add_f32_e32 v150, v150, v151
	v_lshlrev_b32_e32 v151, 16, v178
	v_and_b32_e32 v154, 0xffff0000, v178
	v_add_f32_e32 v151, v151, v154
	v_lshlrev_b32_e32 v154, 16, v179
	v_and_b32_e32 v155, 0xffff0000, v179
	v_add_f32_e32 v154, v154, v155
	v_add_f32_e32 v151, v151, v154
	v_add_f32_e32 v150, v150, v151
	v_mov_b32_e32 v151, v150
	s_nop 1
	v_permlane16_swap_b32_e32 v150, v151
	v_add_f32_e32 v157, v150, v151
	v_lshlrev_b32_e32 v150, 16, v180
	v_and_b32_e32 v151, 0xffff0000, v180
	v_add_f32_e32 v150, v150, v151
	v_lshlrev_b32_e32 v151, 16, v181
	v_and_b32_e32 v154, 0xffff0000, v181
	v_add_f32_e32 v151, v151, v154
	v_add_f32_e32 v150, v150, v151
	v_lshlrev_b32_e32 v151, 16, v182
	v_and_b32_e32 v154, 0xffff0000, v182
	v_add_f32_e32 v151, v151, v154
	v_lshlrev_b32_e32 v154, 16, v183
	v_and_b32_e32 v155, 0xffff0000, v183
	v_add_f32_e32 v154, v154, v155
	s_lshl_b32 s13, s2, 8
	s_mul_i32 s8, s15, 0xfffff400
	v_add_f32_e32 v151, v151, v154
	s_add_i32 s8, s8, s13
	v_add_f32_e32 v150, v150, v151
	v_fmamk_f32 v0, v0, 0x3a000000, v240
	v_mov_b32_e32 v151, v150
	v_or_b32_e32 v176, s8, v165
	v_rsq_f32_e32 v0, v0
	v_permlane16_swap_b32_e32 v150, v151
	v_ashrrev_i32_e32 v177, 31, v176
	v_add_f32_e32 v154, v150, v151
	v_add_u32_e32 v150, s3, v156
	v_lshl_add_u64 v[152:153], v[176:177], 1, v[152:153]
	s_movk_i32 s3, 0x1800
	v_mad_i64_i32 v[180:181], s[8:9], v150, s3, v[152:153]
	s_and_b32 s3, s2, -4
	v_mov_b32_e32 v174, v173
	v_mov_b32_e32 v172, v171
	v_mov_b32_e32 v170, v169
	v_mov_b32_e32 v168, v161
	v_mov_b32_e32 v160, v159
	v_mov_b32_e32 v158, v157
	v_mov_b32_e32 v155, v154
	s_cmp_eq_u32 s3, 4
	v_permlane32_swap_b32_e32 v173, v174
	v_permlane32_swap_b32_e32 v171, v172
	v_permlane32_swap_b32_e32 v169, v170
	v_permlane32_swap_b32_e32 v161, v168
	v_permlane32_swap_b32_e32 v159, v160
	v_permlane32_swap_b32_e32 v157, v158
	v_permlane32_swap_b32_e32 v154, v155
	v_ashrrev_i32_e32 v151, 31, v150
	v_pk_mul_f32 v[128:129], v[128:129], v[0:1] op_sel_hi:[1,0]
	v_pk_mul_f32 v[126:127], v[126:127], v[0:1] op_sel_hi:[1,0]
	v_pk_mul_f32 v[124:125], v[124:125], v[0:1] op_sel_hi:[1,0]
	v_pk_mul_f32 v[122:123], v[122:123], v[0:1] op_sel_hi:[1,0]
	v_cvt_pk_bf16_f32 v176, v126, v127
	v_cvt_pk_bf16_f32 v177, v128, v129
	v_pk_mul_f32 v[120:121], v[120:121], v[0:1] op_sel_hi:[1,0]
	v_cvt_pk_bf16_f32 v178, v122, v123
	v_cvt_pk_bf16_f32 v179, v124, v125
	v_pk_mul_f32 v[118:119], v[118:119], v[0:1] op_sel_hi:[1,0]
	v_pk_mul_f32 v[116:117], v[116:117], v[0:1] op_sel_hi:[1,0]
	v_pk_mul_f32 v[114:115], v[114:115], v[0:1] op_sel_hi:[1,0]
	s_cselect_b64 s[16:17], -1, 0
	s_cmp_lg_u32 s3, 4
	ds_bpermute_b32 v206, v255, v176
	ds_bpermute_b32 v207, v255, v177
	ds_bpermute_b32 v208, v255, v178
	ds_bpermute_b32 v209, v255, v179
	s_nop 1
	v_cvt_pk_bf16_f32 v176, v118, v119
	v_cvt_pk_bf16_f32 v177, v120, v121
	v_cvt_pk_bf16_f32 v178, v114, v115
	v_cvt_pk_bf16_f32 v179, v116, v117
	ds_bpermute_b32 v244, v255, v176
	ds_bpermute_b32 v245, v255, v177
	ds_bpermute_b32 v246, v255, v178
	ds_bpermute_b32 v247, v255, v179
	v_lshl_add_u64 v[248:249], v[180:181], 0, v[252:253]
	s_waitcnt lgkmcnt(4)
	global_store_dwordx4 v[248:249], v[206:209], off
	s_cbranch_scc1 .LBB0_514
	v_mul_f32_e32 v0, v127, v127
	v_mul_f32_e32 v123, v123, v123
	v_mul_f32_e32 v119, v119, v119
	v_mul_f32_e32 v115, v115, v115
	v_fmac_f32_e32 v0, v126, v126
	v_mul_f32_e32 v126, v129, v129
	v_fmac_f32_e32 v123, v122, v122
	v_mul_f32_e32 v122, v125, v125
	v_fmac_f32_e32 v119, v118, v118
	v_mul_f32_e32 v118, v121, v121
	v_fmac_f32_e32 v115, v114, v114
	v_mul_f32_e32 v114, v117, v117
	v_fmac_f32_e32 v126, v128, v128
	v_fmac_f32_e32 v122, v124, v124
	v_fmac_f32_e32 v118, v120, v120
	v_fmac_f32_e32 v114, v116, v116
	v_add_f32_e32 v0, v0, v126
	v_add_f32_e32 v122, v123, v122
	v_add_f32_e32 v118, v119, v118
	v_add_f32_e32 v114, v115, v114
	v_add_f32_e32 v0, v0, v122
	v_add_f32_e32 v115, v118, v114
	v_mov_b32_e32 v114, v0
	v_mov_b32_e32 v116, v115
	s_nop 0
	v_permlane16_swap_b32_e32 v0, v114
	v_permlane16_swap_b32_e32 v115, v116
	v_add_f32_e32 v0, v0, v114
	v_add_f32_e32 v115, v115, v116
	v_mov_b32_e32 v114, v0
	v_mov_b32_e32 v116, v115
	s_nop 0
	v_permlane32_swap_b32_e32 v0, v114
	v_permlane32_swap_b32_e32 v115, v116
	s_and_saveexec_b64 s[8:9], s[4:5]
	s_cbranch_execz .LBB0_513
	v_add_f32_e32 v116, v115, v116
	v_add_f32_e32 v0, v0, v114
	v_lshlrev_b64 v[114:115], 7, v[150:151]
	v_lshl_add_u64 v[114:115], v[138:139], 0, v[114:115]
	s_lshl_b32 s36, s2, 3
	s_mov_b32 s37, s40
	v_lshl_add_u64 v[114:115], s[36:37], 2, v[114:115]
	s_lshl_b32 s36, s27, 2
	v_lshl_add_u64 v[114:115], v[114:115], 0, s[36:37]
	global_store_dword v[114:115], v0, off offset:-128
	global_store_dword v[114:115], v116, off offset:-112

.LBB0_514:
	v_add_f32_e32 v0, v173, v174
	v_fmamk_f32 v0, v0, 0x3a000000, v240
	v_rsq_f32_e32 v0, v0
	v_or_b32_e32 v114, 16, v150
	s_movk_i32 s3, 0x1800
	v_mad_i64_i32 v[120:121], s[8:9], v114, s3, v[152:153]
	v_pk_mul_f32 v[112:113], v[112:113], v[0:1] op_sel_hi:[1,0]
	v_pk_mul_f32 v[110:111], v[110:111], v[0:1] op_sel_hi:[1,0]
	v_pk_mul_f32 v[108:109], v[108:109], v[0:1] op_sel_hi:[1,0]
	v_pk_mul_f32 v[106:107], v[106:107], v[0:1] op_sel_hi:[1,0]
	v_pk_mul_f32 v[104:105], v[104:105], v[0:1] op_sel_hi:[1,0]
	v_pk_mul_f32 v[102:103], v[102:103], v[0:1] op_sel_hi:[1,0]
	v_pk_mul_f32 v[100:101], v[100:101], v[0:1] op_sel_hi:[1,0]
	v_pk_mul_f32 v[98:99], v[98:99], v[0:1] op_sel_hi:[1,0]
	v_cndmask_b32_e64 v0, 0, 1, s[16:17]
	v_cvt_pk_bf16_f32 v116, v110, v111
	v_cvt_pk_bf16_f32 v117, v112, v113
	v_cvt_pk_bf16_f32 v118, v106, v107
	v_cvt_pk_bf16_f32 v119, v108, v109
	v_cmp_ne_u32_e64 s[8:9], 1, v0
	s_andn2_b64 vcc, exec, s[16:17]
	s_waitcnt lgkmcnt(0)
	global_store_dwordx4 v[248:249], v[244:247], off offset:256
	ds_bpermute_b32 v206, v255, v116
	ds_bpermute_b32 v207, v255, v117
	ds_bpermute_b32 v208, v255, v118
	ds_bpermute_b32 v209, v255, v119
	s_nop 1
	v_cvt_pk_bf16_f32 v116, v102, v103
	v_cvt_pk_bf16_f32 v117, v104, v105
	v_cvt_pk_bf16_f32 v118, v98, v99
	v_cvt_pk_bf16_f32 v119, v100, v101
	ds_bpermute_b32 v244, v255, v116
	ds_bpermute_b32 v245, v255, v117
	ds_bpermute_b32 v246, v255, v118
	ds_bpermute_b32 v247, v255, v119
	v_lshl_add_u64 v[248:249], v[120:121], 0, v[252:253]
	s_waitcnt lgkmcnt(4)
	global_store_dwordx4 v[248:249], v[206:209], off
	s_cbranch_vccnz .LBB0_518
	v_mul_f32_e32 v0, v111, v111
	v_mul_f32_e32 v107, v107, v107
	v_mul_f32_e32 v103, v103, v103
	v_mul_f32_e32 v99, v99, v99
	v_fmac_f32_e32 v0, v110, v110
	v_mul_f32_e32 v110, v113, v113
	v_fmac_f32_e32 v107, v106, v106
	v_mul_f32_e32 v106, v109, v109
	v_fmac_f32_e32 v103, v102, v102
	v_mul_f32_e32 v102, v105, v105
	v_fmac_f32_e32 v99, v98, v98
	v_mul_f32_e32 v98, v101, v101
	v_fmac_f32_e32 v110, v112, v112
	v_fmac_f32_e32 v106, v108, v108
	v_fmac_f32_e32 v102, v104, v104
	v_fmac_f32_e32 v98, v100, v100
	v_add_f32_e32 v0, v0, v110
	v_add_f32_e32 v106, v107, v106
	v_add_f32_e32 v102, v103, v102
	v_add_f32_e32 v98, v99, v98
	v_add_f32_e32 v0, v0, v106
	v_add_f32_e32 v99, v102, v98
	v_mov_b32_e32 v98, v0
	v_mov_b32_e32 v100, v99
	s_nop 0
	v_permlane16_swap_b32_e32 v0, v98
	v_permlane16_swap_b32_e32 v99, v100
	v_add_f32_e32 v0, v0, v98
	v_add_f32_e32 v99, v99, v100
	v_mov_b32_e32 v98, v0
	v_mov_b32_e32 v100, v99
	s_nop 0
	v_permlane32_swap_b32_e32 v0, v98
	v_permlane32_swap_b32_e32 v99, v100
	s_and_saveexec_b64 s[16:17], s[4:5]
	s_cbranch_execz .LBB0_517
	v_ashrrev_i32_e32 v115, 31, v114
	v_add_f32_e32 v100, v99, v100
	v_add_f32_e32 v0, v0, v98
	v_lshlrev_b64 v[98:99], 7, v[114:115]
	v_lshl_add_u64 v[98:99], v[138:139], 0, v[98:99]
	s_lshl_b32 s36, s2, 3
	s_mov_b32 s37, s40
	v_lshl_add_u64 v[98:99], s[36:37], 2, v[98:99]
	s_lshl_b32 s36, s27, 2
	v_lshl_add_u64 v[98:99], v[98:99], 0, s[36:37]
	global_store_dword v[98:99], v0, off offset:-128
	global_store_dword v[98:99], v100, off offset:-112

.LBB0_518:
	v_add_f32_e32 v0, v171, v172
	v_fmamk_f32 v0, v0, 0x3a000000, v240
	v_rsq_f32_e32 v0, v0
	v_or_b32_e32 v98, 32, v150
	v_mad_i64_i32 v[104:105], s[16:17], v98, s3, v[152:153]
	v_pk_mul_f32 v[96:97], v[96:97], v[0:1] op_sel_hi:[1,0]
	v_pk_mul_f32 v[94:95], v[94:95], v[0:1] op_sel_hi:[1,0]
	v_pk_mul_f32 v[92:93], v[92:93], v[0:1] op_sel_hi:[1,0]
	v_pk_mul_f32 v[90:91], v[90:91], v[0:1] op_sel_hi:[1,0]
	v_cvt_pk_bf16_f32 v100, v94, v95
	v_cvt_pk_bf16_f32 v101, v96, v97
	v_pk_mul_f32 v[88:89], v[88:89], v[0:1] op_sel_hi:[1,0]
	v_cvt_pk_bf16_f32 v102, v90, v91
	v_cvt_pk_bf16_f32 v103, v92, v93
	v_pk_mul_f32 v[86:87], v[86:87], v[0:1] op_sel_hi:[1,0]
	v_pk_mul_f32 v[84:85], v[84:85], v[0:1] op_sel_hi:[1,0]
	v_pk_mul_f32 v[82:83], v[82:83], v[0:1] op_sel_hi:[1,0]
	s_and_b64 vcc, exec, s[8:9]
	s_waitcnt lgkmcnt(0)
	global_store_dwordx4 v[248:249], v[244:247], off offset:256
	ds_bpermute_b32 v206, v255, v100
	ds_bpermute_b32 v207, v255, v101
	ds_bpermute_b32 v208, v255, v102
	ds_bpermute_b32 v209, v255, v103
	s_nop 1
	v_cvt_pk_bf16_f32 v100, v86, v87
	v_cvt_pk_bf16_f32 v101, v88, v89
	v_cvt_pk_bf16_f32 v102, v82, v83
	v_cvt_pk_bf16_f32 v103, v84, v85
	ds_bpermute_b32 v244, v255, v100
	ds_bpermute_b32 v245, v255, v101
	ds_bpermute_b32 v246, v255, v102
	ds_bpermute_b32 v247, v255, v103
	v_lshl_add_u64 v[248:249], v[104:105], 0, v[252:253]
	s_waitcnt lgkmcnt(4)
	global_store_dwordx4 v[248:249], v[206:209], off
	s_cbranch_vccnz .LBB0_522
	v_mul_f32_e32 v0, v95, v95
	v_mul_f32_e32 v91, v91, v91
	v_mul_f32_e32 v87, v87, v87
	v_mul_f32_e32 v83, v83, v83
	v_fmac_f32_e32 v0, v94, v94
	v_mul_f32_e32 v94, v97, v97
	v_fmac_f32_e32 v91, v90, v90
	v_mul_f32_e32 v90, v93, v93
	v_fmac_f32_e32 v87, v86, v86
	v_mul_f32_e32 v86, v89, v89
	v_fmac_f32_e32 v83, v82, v82
	v_mul_f32_e32 v82, v85, v85
	v_fmac_f32_e32 v94, v96, v96
	v_fmac_f32_e32 v90, v92, v92
	v_fmac_f32_e32 v86, v88, v88
	v_fmac_f32_e32 v82, v84, v84
	v_add_f32_e32 v0, v0, v94
	v_add_f32_e32 v90, v91, v90
	v_add_f32_e32 v86, v87, v86
	v_add_f32_e32 v82, v83, v82
	v_add_f32_e32 v0, v0, v90
	v_add_f32_e32 v83, v86, v82
	v_mov_b32_e32 v82, v0
	v_mov_b32_e32 v84, v83
	s_nop 0
	v_permlane16_swap_b32_e32 v0, v82
	v_permlane16_swap_b32_e32 v83, v84
	v_add_f32_e32 v0, v0, v82
	v_add_f32_e32 v83, v83, v84
	v_mov_b32_e32 v82, v0
	v_mov_b32_e32 v84, v83
	s_nop 0
	v_permlane32_swap_b32_e32 v0, v82
	v_permlane32_swap_b32_e32 v83, v84
	s_and_saveexec_b64 s[16:17], s[4:5]
	s_cbranch_execz .LBB0_521
	v_ashrrev_i32_e32 v99, 31, v98
	v_add_f32_e32 v84, v83, v84
	v_add_f32_e32 v0, v0, v82
	v_lshlrev_b64 v[82:83], 7, v[98:99]
	v_lshl_add_u64 v[82:83], v[138:139], 0, v[82:83]
	s_lshl_b32 s36, s2, 3
	s_mov_b32 s37, s40
	v_lshl_add_u64 v[82:83], s[36:37], 2, v[82:83]
	s_lshl_b32 s36, s27, 2
	v_lshl_add_u64 v[82:83], v[82:83], 0, s[36:37]
	global_store_dword v[82:83], v0, off offset:-128
	global_store_dword v[82:83], v84, off offset:-112

.LBB0_522:
	v_add_f32_e32 v0, v169, v170
	v_fmamk_f32 v0, v0, 0x3a000000, v240
	v_rsq_f32_e32 v0, v0
	v_or_b32_e32 v82, 48, v150
	v_mad_i64_i32 v[88:89], s[16:17], v82, s3, v[152:153]
	v_pk_mul_f32 v[80:81], v[80:81], v[0:1] op_sel_hi:[1,0]
	v_pk_mul_f32 v[78:79], v[78:79], v[0:1] op_sel_hi:[1,0]
	v_pk_mul_f32 v[76:77], v[76:77], v[0:1] op_sel_hi:[1,0]
	v_pk_mul_f32 v[74:75], v[74:75], v[0:1] op_sel_hi:[1,0]
	v_cvt_pk_bf16_f32 v84, v78, v79
	v_cvt_pk_bf16_f32 v85, v80, v81
	v_pk_mul_f32 v[72:73], v[72:73], v[0:1] op_sel_hi:[1,0]
	v_cvt_pk_bf16_f32 v86, v74, v75
	v_cvt_pk_bf16_f32 v87, v76, v77
	v_pk_mul_f32 v[70:71], v[70:71], v[0:1] op_sel_hi:[1,0]
	v_pk_mul_f32 v[68:69], v[68:69], v[0:1] op_sel_hi:[1,0]
	v_pk_mul_f32 v[66:67], v[66:67], v[0:1] op_sel_hi:[1,0]
	s_and_b64 vcc, exec, s[8:9]
	s_waitcnt lgkmcnt(0)
	global_store_dwordx4 v[248:249], v[244:247], off offset:256
	ds_bpermute_b32 v206, v255, v84
	ds_bpermute_b32 v207, v255, v85
	ds_bpermute_b32 v208, v255, v86
	ds_bpermute_b32 v209, v255, v87
	s_nop 1
	v_cvt_pk_bf16_f32 v84, v70, v71
	v_cvt_pk_bf16_f32 v85, v72, v73
	v_cvt_pk_bf16_f32 v86, v66, v67
	v_cvt_pk_bf16_f32 v87, v68, v69
	ds_bpermute_b32 v244, v255, v84
	ds_bpermute_b32 v245, v255, v85
	ds_bpermute_b32 v246, v255, v86
	ds_bpermute_b32 v247, v255, v87
	v_lshl_add_u64 v[248:249], v[88:89], 0, v[252:253]
	s_waitcnt lgkmcnt(4)
	global_store_dwordx4 v[248:249], v[206:209], off
	s_cbranch_vccnz .LBB0_526
	v_mul_f32_e32 v0, v79, v79
	v_mul_f32_e32 v75, v75, v75
	v_mul_f32_e32 v71, v71, v71
	v_mul_f32_e32 v67, v67, v67
	v_fmac_f32_e32 v0, v78, v78
	v_mul_f32_e32 v78, v81, v81
	v_fmac_f32_e32 v75, v74, v74
	v_mul_f32_e32 v74, v77, v77
	v_fmac_f32_e32 v71, v70, v70
	v_mul_f32_e32 v70, v73, v73
	v_fmac_f32_e32 v67, v66, v66
	v_mul_f32_e32 v66, v69, v69
	v_fmac_f32_e32 v78, v80, v80
	v_fmac_f32_e32 v74, v76, v76
	v_fmac_f32_e32 v70, v72, v72
	v_fmac_f32_e32 v66, v68, v68
	v_add_f32_e32 v0, v0, v78
	v_add_f32_e32 v74, v75, v74
	v_add_f32_e32 v70, v71, v70
	v_add_f32_e32 v66, v67, v66
	v_add_f32_e32 v0, v0, v74
	v_add_f32_e32 v67, v70, v66
	v_mov_b32_e32 v66, v0
	v_mov_b32_e32 v68, v67
	s_nop 0
	v_permlane16_swap_b32_e32 v0, v66
	v_permlane16_swap_b32_e32 v67, v68
	v_add_f32_e32 v0, v0, v66
	v_add_f32_e32 v67, v67, v68
	v_mov_b32_e32 v66, v0
	v_mov_b32_e32 v68, v67
	s_nop 0
	v_permlane32_swap_b32_e32 v0, v66
	v_permlane32_swap_b32_e32 v67, v68
	s_and_saveexec_b64 s[16:17], s[4:5]
	s_cbranch_execz .LBB0_525
	v_ashrrev_i32_e32 v83, 31, v82
	v_add_f32_e32 v68, v67, v68
	v_add_f32_e32 v0, v0, v66
	v_lshlrev_b64 v[66:67], 7, v[82:83]
	v_lshl_add_u64 v[66:67], v[138:139], 0, v[66:67]
	s_lshl_b32 s36, s2, 3
	s_mov_b32 s37, s40
	v_lshl_add_u64 v[66:67], s[36:37], 2, v[66:67]
	s_lshl_b32 s36, s27, 2
	v_lshl_add_u64 v[66:67], v[66:67], 0, s[36:37]
	global_store_dword v[66:67], v0, off offset:-128
	global_store_dword v[66:67], v68, off offset:-112

.LBB0_526:
	v_add_f32_e32 v0, v161, v168
	v_fmamk_f32 v0, v0, 0x3a000000, v240
	v_rsq_f32_e32 v0, v0
	v_add_u32_e32 v66, 0x80, v150
	v_mad_i64_i32 v[72:73], s[16:17], v66, s3, v[152:153]
	v_pk_mul_f32 v[64:65], v[64:65], v[0:1] op_sel_hi:[1,0]
	v_pk_mul_f32 v[62:63], v[62:63], v[0:1] op_sel_hi:[1,0]
	v_pk_mul_f32 v[60:61], v[60:61], v[0:1] op_sel_hi:[1,0]
	v_pk_mul_f32 v[58:59], v[58:59], v[0:1] op_sel_hi:[1,0]
	v_cvt_pk_bf16_f32 v68, v62, v63
	v_cvt_pk_bf16_f32 v69, v64, v65
	v_pk_mul_f32 v[56:57], v[56:57], v[0:1] op_sel_hi:[1,0]
	v_cvt_pk_bf16_f32 v70, v58, v59
	v_cvt_pk_bf16_f32 v71, v60, v61
	v_pk_mul_f32 v[54:55], v[54:55], v[0:1] op_sel_hi:[1,0]
	v_pk_mul_f32 v[52:53], v[52:53], v[0:1] op_sel_hi:[1,0]
	v_pk_mul_f32 v[50:51], v[50:51], v[0:1] op_sel_hi:[1,0]
	s_and_b64 vcc, exec, s[8:9]
	s_waitcnt lgkmcnt(0)
	global_store_dwordx4 v[248:249], v[244:247], off offset:256
	ds_bpermute_b32 v206, v255, v68
	ds_bpermute_b32 v207, v255, v69
	ds_bpermute_b32 v208, v255, v70
	ds_bpermute_b32 v209, v255, v71
	s_nop 1
	v_cvt_pk_bf16_f32 v68, v54, v55
	v_cvt_pk_bf16_f32 v69, v56, v57
	v_cvt_pk_bf16_f32 v70, v50, v51
	v_cvt_pk_bf16_f32 v71, v52, v53
	ds_bpermute_b32 v244, v255, v68
	ds_bpermute_b32 v245, v255, v69
	ds_bpermute_b32 v246, v255, v70
	ds_bpermute_b32 v247, v255, v71
	v_lshl_add_u64 v[248:249], v[72:73], 0, v[252:253]
	s_waitcnt lgkmcnt(4)
	global_store_dwordx4 v[248:249], v[206:209], off
	s_cbranch_vccnz .LBB0_530
	v_mul_f32_e32 v0, v63, v63
	v_mul_f32_e32 v59, v59, v59
	v_mul_f32_e32 v55, v55, v55
	v_mul_f32_e32 v51, v51, v51
	v_fmac_f32_e32 v0, v62, v62
	v_mul_f32_e32 v62, v65, v65
	v_fmac_f32_e32 v59, v58, v58
	v_mul_f32_e32 v58, v61, v61
	v_fmac_f32_e32 v55, v54, v54
	v_mul_f32_e32 v54, v57, v57
	v_fmac_f32_e32 v51, v50, v50
	v_mul_f32_e32 v50, v53, v53
	v_fmac_f32_e32 v62, v64, v64
	v_fmac_f32_e32 v58, v60, v60
	v_fmac_f32_e32 v54, v56, v56
	v_fmac_f32_e32 v50, v52, v52
	v_add_f32_e32 v0, v0, v62
	v_add_f32_e32 v58, v59, v58
	v_add_f32_e32 v54, v55, v54
	v_add_f32_e32 v50, v51, v50
	v_add_f32_e32 v0, v0, v58
	v_add_f32_e32 v51, v54, v50
	v_mov_b32_e32 v50, v0
	v_mov_b32_e32 v52, v51
	s_nop 0
	v_permlane16_swap_b32_e32 v0, v50
	v_permlane16_swap_b32_e32 v51, v52
	v_add_f32_e32 v0, v0, v50
	v_add_f32_e32 v51, v51, v52
	v_mov_b32_e32 v50, v0
	v_mov_b32_e32 v52, v51
	s_nop 0
	v_permlane32_swap_b32_e32 v0, v50
	v_permlane32_swap_b32_e32 v51, v52
	s_and_saveexec_b64 s[16:17], s[4:5]
	s_cbranch_execz .LBB0_529
	v_ashrrev_i32_e32 v67, 31, v66
	v_add_f32_e32 v52, v51, v52
	v_add_f32_e32 v0, v0, v50
	v_lshlrev_b64 v[50:51], 7, v[66:67]
	v_lshl_add_u64 v[50:51], v[138:139], 0, v[50:51]
	s_lshl_b32 s36, s2, 3
	s_mov_b32 s37, s40
	v_lshl_add_u64 v[50:51], s[36:37], 2, v[50:51]
	s_lshl_b32 s36, s27, 2
	v_lshl_add_u64 v[50:51], v[50:51], 0, s[36:37]
	global_store_dword v[50:51], v0, off offset:-128
	global_store_dword v[50:51], v52, off offset:-112

.LBB0_530:
	v_add_f32_e32 v0, v159, v160
	v_fmamk_f32 v0, v0, 0x3a000000, v240
	v_rsq_f32_e32 v0, v0
	v_add_u32_e32 v50, 0x90, v150
	v_mad_i64_i32 v[56:57], s[16:17], v50, s3, v[152:153]
	v_pk_mul_f32 v[48:49], v[48:49], v[0:1] op_sel_hi:[1,0]
	v_pk_mul_f32 v[46:47], v[46:47], v[0:1] op_sel_hi:[1,0]
	v_pk_mul_f32 v[44:45], v[44:45], v[0:1] op_sel_hi:[1,0]
	v_pk_mul_f32 v[42:43], v[42:43], v[0:1] op_sel_hi:[1,0]
	v_cvt_pk_bf16_f32 v52, v46, v47
	v_cvt_pk_bf16_f32 v53, v48, v49
	v_pk_mul_f32 v[40:41], v[40:41], v[0:1] op_sel_hi:[1,0]
	v_cvt_pk_bf16_f32 v54, v42, v43
	v_cvt_pk_bf16_f32 v55, v44, v45
	v_pk_mul_f32 v[38:39], v[38:39], v[0:1] op_sel_hi:[1,0]
	v_pk_mul_f32 v[36:37], v[36:37], v[0:1] op_sel_hi:[1,0]
	v_pk_mul_f32 v[34:35], v[34:35], v[0:1] op_sel_hi:[1,0]
	s_and_b64 vcc, exec, s[8:9]
	s_waitcnt lgkmcnt(0)
	global_store_dwordx4 v[248:249], v[244:247], off offset:256
	ds_bpermute_b32 v206, v255, v52
	ds_bpermute_b32 v207, v255, v53
	ds_bpermute_b32 v208, v255, v54
	ds_bpermute_b32 v209, v255, v55
	s_nop 1
	v_cvt_pk_bf16_f32 v52, v38, v39
	v_cvt_pk_bf16_f32 v53, v40, v41
	v_cvt_pk_bf16_f32 v54, v34, v35
	v_cvt_pk_bf16_f32 v55, v36, v37
	ds_bpermute_b32 v244, v255, v52
	ds_bpermute_b32 v245, v255, v53
	ds_bpermute_b32 v246, v255, v54
	ds_bpermute_b32 v247, v255, v55
	v_lshl_add_u64 v[248:249], v[56:57], 0, v[252:253]
	s_waitcnt lgkmcnt(4)
	global_store_dwordx4 v[248:249], v[206:209], off
	s_cbranch_vccnz .LBB0_534
	v_mul_f32_e32 v0, v47, v47
	v_mul_f32_e32 v43, v43, v43
	v_mul_f32_e32 v39, v39, v39
	v_mul_f32_e32 v35, v35, v35
	v_fmac_f32_e32 v0, v46, v46
	v_mul_f32_e32 v46, v49, v49
	v_fmac_f32_e32 v43, v42, v42
	v_mul_f32_e32 v42, v45, v45
	v_fmac_f32_e32 v39, v38, v38
	v_mul_f32_e32 v38, v41, v41
	v_fmac_f32_e32 v35, v34, v34
	v_mul_f32_e32 v34, v37, v37
	v_fmac_f32_e32 v46, v48, v48
	v_fmac_f32_e32 v42, v44, v44
	v_fmac_f32_e32 v38, v40, v40
	v_fmac_f32_e32 v34, v36, v36
	v_add_f32_e32 v0, v0, v46
	v_add_f32_e32 v42, v43, v42
	v_add_f32_e32 v38, v39, v38
	v_add_f32_e32 v34, v35, v34
	v_add_f32_e32 v0, v0, v42
	v_add_f32_e32 v35, v38, v34
	v_mov_b32_e32 v34, v0
	v_mov_b32_e32 v36, v35
	s_nop 0
	v_permlane16_swap_b32_e32 v0, v34
	v_permlane16_swap_b32_e32 v35, v36
	v_add_f32_e32 v0, v0, v34
	v_add_f32_e32 v35, v35, v36
	v_mov_b32_e32 v34, v0
	v_mov_b32_e32 v36, v35
	s_nop 0
	v_permlane32_swap_b32_e32 v0, v34
	v_permlane32_swap_b32_e32 v35, v36
	s_and_saveexec_b64 s[16:17], s[4:5]
	s_cbranch_execz .LBB0_533
	v_ashrrev_i32_e32 v51, 31, v50
	v_add_f32_e32 v36, v35, v36
	v_add_f32_e32 v0, v0, v34
	v_lshlrev_b64 v[34:35], 7, v[50:51]
	v_lshl_add_u64 v[34:35], v[138:139], 0, v[34:35]
	s_lshl_b32 s36, s2, 3
	s_mov_b32 s37, s40
	v_lshl_add_u64 v[34:35], s[36:37], 2, v[34:35]
	s_lshl_b32 s36, s27, 2
	v_lshl_add_u64 v[34:35], v[34:35], 0, s[36:37]
	global_store_dword v[34:35], v0, off offset:-128
	global_store_dword v[34:35], v36, off offset:-112

.LBB0_534:
	v_add_f32_e32 v0, v157, v158
	v_fmamk_f32 v0, v0, 0x3a000000, v240
	v_rsq_f32_e32 v0, v0
	v_add_u32_e32 v34, 0xa0, v150
	v_mad_i64_i32 v[40:41], s[16:17], v34, s3, v[152:153]
	v_pk_mul_f32 v[32:33], v[32:33], v[0:1] op_sel_hi:[1,0]
	v_pk_mul_f32 v[30:31], v[30:31], v[0:1] op_sel_hi:[1,0]
	v_pk_mul_f32 v[28:29], v[28:29], v[0:1] op_sel_hi:[1,0]
	v_pk_mul_f32 v[26:27], v[26:27], v[0:1] op_sel_hi:[1,0]
	v_cvt_pk_bf16_f32 v36, v30, v31
	v_cvt_pk_bf16_f32 v37, v32, v33
	v_pk_mul_f32 v[24:25], v[24:25], v[0:1] op_sel_hi:[1,0]
	v_cvt_pk_bf16_f32 v38, v26, v27
	v_cvt_pk_bf16_f32 v39, v28, v29
	v_pk_mul_f32 v[22:23], v[22:23], v[0:1] op_sel_hi:[1,0]
	v_pk_mul_f32 v[20:21], v[20:21], v[0:1] op_sel_hi:[1,0]
	v_pk_mul_f32 v[18:19], v[18:19], v[0:1] op_sel_hi:[1,0]
	s_and_b64 vcc, exec, s[8:9]
	s_waitcnt lgkmcnt(0)
	global_store_dwordx4 v[248:249], v[244:247], off offset:256
	ds_bpermute_b32 v206, v255, v36
	ds_bpermute_b32 v207, v255, v37
	ds_bpermute_b32 v208, v255, v38
	ds_bpermute_b32 v209, v255, v39
	s_nop 1
	v_cvt_pk_bf16_f32 v36, v22, v23
	v_cvt_pk_bf16_f32 v37, v24, v25
	v_cvt_pk_bf16_f32 v38, v18, v19
	v_cvt_pk_bf16_f32 v39, v20, v21
	ds_bpermute_b32 v244, v255, v36
	ds_bpermute_b32 v245, v255, v37
	ds_bpermute_b32 v246, v255, v38
	ds_bpermute_b32 v247, v255, v39
	v_lshl_add_u64 v[248:249], v[40:41], 0, v[252:253]
	s_waitcnt lgkmcnt(4)
	global_store_dwordx4 v[248:249], v[206:209], off
	s_cbranch_vccnz .LBB0_538
	v_mul_f32_e32 v0, v31, v31
	v_mul_f32_e32 v27, v27, v27
	v_mul_f32_e32 v23, v23, v23
	v_mul_f32_e32 v19, v19, v19
	v_fmac_f32_e32 v0, v30, v30
	v_mul_f32_e32 v30, v33, v33
	v_fmac_f32_e32 v27, v26, v26
	v_mul_f32_e32 v26, v29, v29
	v_fmac_f32_e32 v23, v22, v22
	v_mul_f32_e32 v22, v25, v25
	v_fmac_f32_e32 v19, v18, v18
	v_mul_f32_e32 v18, v21, v21
	v_fmac_f32_e32 v30, v32, v32
	v_fmac_f32_e32 v26, v28, v28
	v_fmac_f32_e32 v22, v24, v24
	v_fmac_f32_e32 v18, v20, v20
	v_add_f32_e32 v0, v0, v30
	v_add_f32_e32 v26, v27, v26
	v_add_f32_e32 v22, v23, v22
	v_add_f32_e32 v18, v19, v18
	v_add_f32_e32 v0, v0, v26
	v_add_f32_e32 v19, v22, v18
	v_mov_b32_e32 v18, v0
	v_mov_b32_e32 v20, v19
	s_nop 0
	v_permlane16_swap_b32_e32 v0, v18
	v_permlane16_swap_b32_e32 v19, v20
	v_add_f32_e32 v0, v0, v18
	v_add_f32_e32 v19, v19, v20
	v_mov_b32_e32 v18, v0
	v_mov_b32_e32 v20, v19
	s_nop 0
	v_permlane32_swap_b32_e32 v0, v18
	v_permlane32_swap_b32_e32 v19, v20
	s_and_saveexec_b64 s[16:17], s[4:5]
	s_cbranch_execz .LBB0_537
	v_ashrrev_i32_e32 v35, 31, v34
	v_add_f32_e32 v20, v19, v20
	v_add_f32_e32 v0, v0, v18
	v_lshlrev_b64 v[18:19], 7, v[34:35]
	v_lshl_add_u64 v[18:19], v[138:139], 0, v[18:19]
	s_lshl_b32 s36, s2, 3
	s_mov_b32 s37, s40
	v_lshl_add_u64 v[18:19], s[36:37], 2, v[18:19]
	s_lshl_b32 s36, s27, 2
	v_lshl_add_u64 v[18:19], v[18:19], 0, s[36:37]
	global_store_dword v[18:19], v0, off offset:-128
	global_store_dword v[18:19], v20, off offset:-112

.LBB0_538:
	v_add_f32_e32 v0, v154, v155
	v_fmamk_f32 v0, v0, 0x3a000000, v240
	v_rsq_f32_e32 v0, v0
	v_add_u32_e32 v18, 0xb0, v150
	v_mad_i64_i32 v[26:27], s[16:17], v18, s3, v[152:153]
	v_pk_mul_f32 v[12:13], v[12:13], v[0:1] op_sel_hi:[1,0]
	v_pk_mul_f32 v[10:11], v[10:11], v[0:1] op_sel_hi:[1,0]
	v_pk_mul_f32 v[8:9], v[8:9], v[0:1] op_sel_hi:[1,0]
	v_cvt_pk_bf16_f32 v20, v10, v11
	v_cvt_pk_bf16_f32 v21, v12, v13
	v_pk_mul_f32 v[6:7], v[6:7], v[0:1] op_sel_hi:[1,0]
	v_pk_mul_f32 v[4:5], v[4:5], v[0:1] op_sel_hi:[1,0]
	v_cvt_pk_bf16_f32 v22, v6, v7
	v_cvt_pk_bf16_f32 v23, v8, v9
	s_waitcnt lgkmcnt(0)
	global_store_dwordx4 v[248:249], v[244:247], off offset:256
	ds_bpermute_b32 v206, v255, v20
	ds_bpermute_b32 v207, v255, v21
	ds_bpermute_b32 v208, v255, v22
	ds_bpermute_b32 v209, v255, v23
	v_pk_mul_f32 v[14:15], v[14:15], v[0:1] op_sel_hi:[1,0]
	s_and_b64 vcc, exec, s[8:9]
	v_pk_mul_f32 v[20:21], v[2:3], v[0:1] op_sel_hi:[1,0]
	v_pk_mul_f32 v[2:3], v[16:17], v[0:1] op_sel_hi:[1,0]
	v_cvt_pk_bf16_f32 v22, v20, v21
	v_cvt_pk_bf16_f32 v23, v4, v5
	v_cvt_pk_bf16_f32 v24, v14, v15
	s_nop 0
	v_cvt_pk_bf16_f32 v25, v2, v3
	ds_bpermute_b32 v244, v255, v22
	ds_bpermute_b32 v245, v255, v23
	ds_bpermute_b32 v246, v255, v24
	ds_bpermute_b32 v247, v255, v25
	v_lshl_add_u64 v[248:249], v[26:27], 0, v[252:253]
	s_waitcnt lgkmcnt(4)
	global_store_dwordx4 v[248:249], v[206:209], off
	s_waitcnt lgkmcnt(0)
	global_store_dwordx4 v[248:249], v[244:247], off offset:256
	s_cbranch_vccnz .LBB0_542
	v_mul_f32_e32 v0, v11, v11
	v_mul_f32_e32 v7, v7, v7
	v_fmac_f32_e32 v0, v10, v10
	v_mul_f32_e32 v10, v13, v13
	v_fmac_f32_e32 v7, v6, v6
	v_mul_f32_e32 v6, v9, v9
	v_fmac_f32_e32 v10, v12, v12
	v_fmac_f32_e32 v6, v8, v8
	v_add_f32_e32 v0, v0, v10
	v_add_f32_e32 v6, v7, v6
	v_add_f32_e32 v0, v0, v6
	v_mul_f32_e32 v6, v21, v21
	v_mul_f32_e32 v5, v5, v5
	v_fmac_f32_e32 v6, v20, v20
	v_fmac_f32_e32 v5, v4, v4
	v_add_f32_e32 v4, v6, v5
	v_mul_f32_e32 v5, v15, v15
	v_mul_f32_e32 v3, v3, v3
	v_fmac_f32_e32 v5, v14, v14
	v_fmac_f32_e32 v3, v2, v2
	v_add_f32_e32 v2, v5, v3
	v_add_f32_e32 v3, v4, v2
	v_mov_b32_e32 v2, v0
	v_mov_b32_e32 v4, v3
	s_nop 0
	v_permlane16_swap_b32_e32 v0, v2
	v_permlane16_swap_b32_e32 v3, v4
	v_add_f32_e32 v0, v0, v2
	v_add_f32_e32 v3, v3, v4
	v_mov_b32_e32 v2, v0
	v_mov_b32_e32 v4, v3
	s_nop 0
	v_permlane32_swap_b32_e32 v0, v2
	v_permlane32_swap_b32_e32 v3, v4
	s_and_saveexec_b64 s[8:9], s[4:5]
	s_cbranch_execz .LBB0_541
	v_ashrrev_i32_e32 v19, 31, v18
	v_add_f32_e32 v4, v3, v4
	v_add_f32_e32 v0, v0, v2
	v_lshlrev_b64 v[2:3], 7, v[18:19]
	v_lshl_add_u64 v[2:3], v[138:139], 0, v[2:3]
	s_lshl_b32 s2, s2, 3
	s_mov_b32 s3, s40
	v_lshl_add_u64 v[2:3], s[2:3], 2, v[2:3]
	s_lshl_b32 s2, s27, 2
	v_lshl_add_u64 v[2:3], v[2:3], 0, s[2:3]
	global_store_dword v[2:3], v0, off offset:-128
	global_store_dword v[2:3], v4, off offset:-112

.LBB0_591:
	s_or_b64 exec, exec, s[0:1]
	s_waitcnt lgkmcnt(0)
	s_barrier
	v_mov_b32_e32 v244, 0xbab64f3b
	v_not_b32_e32 v245, 31
	v_mov_b32_e32 v246, 0x7fc00000
	v_mov_b32_e32 v247, 0x7f800000
	v_mov_b32_e32 v248, 0xff61b1e6
	v_mov_b32_e32 v249, 0x3c0881c4
.LBB0_592:
	v_readlane_b32 s2, v254, 2
	v_readlane_b32 s3, v254, 3
	s_cmp_ge_i32 s20, s2
	s_cselect_b64 s[0:1], -1, 0
	s_cmp_lt_i32 s20, s3
	s_cselect_b64 s[2:3], -1, 0
	s_and_b64 s[2:3], s[0:1], s[2:3]
	s_mov_b64 s[0:1], -1
	s_and_b64 vcc, exec, s[2:3]
	s_cbranch_vccnz .LBB0_594
	v_readlane_b32 s0, v254, 10
	s_add_i32 s20, s0, 2
	s_mov_b64 s[0:1], 0
